# grid barriers: acquire cache-invalidate issued at arrival instead of after release (off the critical path); EpiMix bias/scale prefetch
# speedup vs baseline: 1.0598x; 1.0147x over previous
; __device__ __forceinline__ unsigned xb_add(unsigned* p, unsigned v) { return __hip_atomic_fetch_add(p, v, __ATOMIC_RELAXED, __HIP_MEMORY_SCOPE_AGENT); }
; __device__ __forceinline__ void xcd_barrier(const XcdBarrier& b) {
;     asm volatile("s_waitcnt vmcnt(0)" ::: "memory");
;     __syncthreads();
;     if (threadIdx.x == 0) {
;         unsigned* bar = b.bar;
;         __builtin_amdgcn_s_waitcnt(0);
;         unsigned nloc = b.st[0], nx = b.st[1];
;         if (nloc == 0u) { xcd_barrier_complete(bar, b.x, nloc, nx); b.st[0] = nloc; b.st[1] = nx; }
;         const unsigned old = xb_add(&bar[XB_XSUB(b.x)], 1u);
;         const unsigned gen = old / nloc;
;         if (old + 1u == (gen + 1u) * nloc) {
.LBB0_129:
	s_or_b64 exec, exec, s[6:7]
	v_cvt_f32_u32_e32 v4, v2
	buffer_inv sc1
	s_waitcnt vmcnt(1)
	v_readfirstlane_b32 s2, v3
	v_sub_u32_e32 v3, 0, v2
	v_rcp_iflag_f32_e32 v4, v4
	v_add_u32_e32 v5, s2, v1
	v_mul_f32_e32 v4, 0x4f7ffffe, v4
	v_cvt_u32_f32_e32 v4, v4
	v_mul_lo_u32 v1, v3, v4
	v_mul_hi_u32 v1, v4, v1
	v_add_u32_e32 v1, v4, v1
	v_mul_hi_u32 v1, v5, v1
	v_mul_lo_u32 v3, v1, v2
	v_sub_u32_e32 v3, v5, v3
	v_add_u32_e32 v4, 1, v1
	v_cmp_ge_u32_e32 vcc, v3, v2
	s_nop 1
	v_cndmask_b32_e32 v1, v1, v4, vcc
	v_sub_u32_e32 v4, v3, v2
	v_cndmask_b32_e32 v3, v3, v4, vcc
	v_add_u32_e32 v4, 1, v1
	v_cmp_ge_u32_e32 vcc, v3, v2
	v_add_u32_e32 v3, 1, v5
	s_nop 0
	v_cndmask_b32_e32 v1, v1, v4, vcc
	v_mul_lo_u32 v4, v2, v1
	v_add_u32_e32 v2, v4, v2
	v_cmp_ne_u32_e32 vcc, v3, v2
	s_and_saveexec_b64 s[2:3], vcc
	s_xor_b64 s[6:7], exec, s[2:3]
	s_cbranch_execz .LBB0_143
	s_waitcnt lgkmcnt(0)
	v_mov_b32_e32 v0, 0x2000
	global_load_dword v0, v0, s[4:5] offset:1024 sc1
	s_add_u32 s12, s4, 0x2400
	s_addc_u32 s13, s5, 0
	s_waitcnt vmcnt(0)
	v_cmp_eq_u32_e32 vcc, v0, v1
	s_and_saveexec_b64 s[8:9], vcc
	s_cbranch_execz .LBB0_142
	s_add_u32 s10, s88, 0x1fa60200
	s_addc_u32 s11, s89, 0
	s_mov_b32 s2, 1
	s_mov_b64 s[14:15], 0
	v_mov_b32_e32 v0, 0
	s_branch .LBB0_133

; __device__ __forceinline__ unsigned xb_ld(unsigned* p)              { return __hip_atomic_load(p, __ATOMIC_RELAXED, __HIP_MEMORY_SCOPE_AGENT); }
; #define XB_SPIN(cond, bar) do { unsigned _sp = 0; while (cond) { __builtin_amdgcn_s_sleep(1); \
;     if ((++_sp & 255u) == 0u) { if (xb_ld(&(bar)[XB_TMO])) break; if (_sp > XB_SPIN_CAP) { atomicAdd(&(bar)[XB_TMO], 1u); break; } } } } while (0)
; __device__ __forceinline__ void xcd_barrier(const XcdBarrier& b) {
;     ...
;         } else {
;             XB_SPIN(xb_ld(&bar[XB_XGEN(b.x)]) == gen, bar);
;             __builtin_amdgcn_fence(__ATOMIC_ACQUIRE, "agent");
;             asm volatile("s_waitcnt vmcnt(0)" ::: "memory");
;         }
.LBB0_142:
	s_or_b64 exec, exec, s[8:9]
	s_waitcnt vmcnt(0)
	s_nop 0
	s_waitcnt vmcnt(0)

; __device__ __forceinline__ unsigned xb_ld(unsigned* p)              { return __hip_atomic_load(p, __ATOMIC_RELAXED, __HIP_MEMORY_SCOPE_AGENT); }
; __device__ __forceinline__ unsigned xb_add(unsigned* p, unsigned v) { return __hip_atomic_fetch_add(p, v, __ATOMIC_RELAXED, __HIP_MEMORY_SCOPE_AGENT); }
; #define XB_SPIN(cond, bar) do { unsigned _sp = 0; while (cond) { __builtin_amdgcn_s_sleep(1); \
;     if ((++_sp & 255u) == 0u) { if (xb_ld(&(bar)[XB_TMO])) break; if (_sp > XB_SPIN_CAP) { atomicAdd(&(bar)[XB_TMO], 1u); break; } } } } while (0)
; __device__ __forceinline__ void xcd_barrier(const XcdBarrier& b) {
;     ...
;             const unsigned og = xb_add(&bar[XB_TOP], 1u);
;             const unsigned tg = og / nx;
;             if (og + 1u == (tg + 1u) * nx) xb_add(&bar[XB_TOPGEN], 1u);
;             else XB_SPIN(xb_ld(&bar[XB_TOPGEN]) == tg, bar);
;             __builtin_amdgcn_fence(__ATOMIC_ACQUIRE, "agent");
;             xb_add(&bar[XB_XGEN(b.x)], 1u);
;             asm volatile("s_waitcnt vmcnt(0)" ::: "memory");
.LBB0_160:
	s_or_b64 exec, exec, s[6:7]
	s_mov_b64 s[2:3], exec
	v_mbcnt_lo_u32_b32 v0, s2, 0
	v_mbcnt_hi_u32_b32 v0, s3, v0
	v_cmp_eq_u32_e32 vcc, 0, v0
	s_waitcnt vmcnt(0)
	s_nop 0
	s_and_saveexec_b64 s[6:7], vcc
	s_cbranch_execz .LBB0_162
	s_bcnt1_i32_b64 s2, s[2:3]
	v_mov_b32_e32 v0, 0x2000
	v_mov_b32_e32 v1, s2
	global_atomic_add v0, v1, s[4:5] offset:1024

; __device__ __forceinline__ unsigned xb_add(unsigned* p, unsigned v) { return __hip_atomic_fetch_add(p, v, __ATOMIC_RELAXED, __HIP_MEMORY_SCOPE_AGENT); }
; __device__ __forceinline__ void xcd_barrier(const XcdBarrier& b) {
;     asm volatile("s_waitcnt vmcnt(0)" ::: "memory");
;     __syncthreads();
;     if (threadIdx.x == 0) {
;         unsigned* bar = b.bar;
;         __builtin_amdgcn_s_waitcnt(0);
;         unsigned nloc = b.st[0], nx = b.st[1];
;         if (nloc == 0u) { xcd_barrier_complete(bar, b.x, nloc, nx); b.st[0] = nloc; b.st[1] = nx; }
;         const unsigned old = xb_add(&bar[XB_XSUB(b.x)], 1u);
;         const unsigned gen = old / nloc;
;         if (old + 1u == (gen + 1u) * nloc) {
.LBB0_299:
	s_or_b64 exec, exec, s[6:7]
	v_cvt_f32_u32_e32 v4, v2
	buffer_inv sc1
	s_waitcnt vmcnt(1)
	v_readfirstlane_b32 s2, v3
	v_sub_u32_e32 v3, 0, v2
	v_rcp_iflag_f32_e32 v4, v4
	v_add_u32_e32 v5, s2, v1
	v_mul_f32_e32 v4, 0x4f7ffffe, v4
	v_cvt_u32_f32_e32 v4, v4
	v_mul_lo_u32 v1, v3, v4
	v_mul_hi_u32 v1, v4, v1
	v_add_u32_e32 v1, v4, v1
	v_mul_hi_u32 v1, v5, v1
	v_mul_lo_u32 v3, v1, v2
	v_sub_u32_e32 v3, v5, v3
	v_add_u32_e32 v4, 1, v1
	v_cmp_ge_u32_e32 vcc, v3, v2
	s_nop 1
	v_cndmask_b32_e32 v1, v1, v4, vcc
	v_sub_u32_e32 v4, v3, v2
	v_cndmask_b32_e32 v3, v3, v4, vcc
	v_add_u32_e32 v4, 1, v1
	v_cmp_ge_u32_e32 vcc, v3, v2
	v_add_u32_e32 v3, 1, v5
	s_nop 0
	v_cndmask_b32_e32 v1, v1, v4, vcc
	v_mul_lo_u32 v4, v2, v1
	v_add_u32_e32 v2, v4, v2
	v_cmp_ne_u32_e32 vcc, v3, v2
	s_and_saveexec_b64 s[2:3], vcc
	s_xor_b64 s[6:7], exec, s[2:3]
	s_cbranch_execz .LBB0_313
	s_waitcnt lgkmcnt(0)
	v_mov_b32_e32 v0, 0x2000
	global_load_dword v0, v0, s[4:5] offset:1024 sc1
	s_add_u32 s12, s4, 0x2400
	s_addc_u32 s13, s5, 0
	s_waitcnt vmcnt(0)
	v_cmp_eq_u32_e32 vcc, v0, v1
	s_and_saveexec_b64 s[8:9], vcc
	s_cbranch_execz .LBB0_312
	s_add_u32 s10, s88, 0x1fa60200
	s_addc_u32 s11, s89, 0
	s_mov_b32 s2, 1
	s_mov_b64 s[24:25], 0
	v_mov_b32_e32 v0, 0
	s_branch .LBB0_303

.LBB0_600:
	ds_read_b128 v[128:131], v188
	ds_read_b128 v[132:135], v188 offset:1024
	ds_read_b128 v[136:139], v188 offset:2048
	ds_read_b128 v[140:143], v188 offset:3072
	s_add_u32 s30, s6, 0xfff80080
	s_addc_u32 s31, s7, -1
	s_cmp_eq_u32 s51, 4
	s_cselect_b32 s35, s25, s31
	s_cselect_b32 s34, s24, s30
	s_cselect_b32 s31, s2, s15
	s_cselect_b32 s30, s3, s13
	v_lshl_add_u64 v[202:203], s[6:7], 0, v[160:161]
	s_add_i32 m0, s29, 0xc000
	ds_read_b128 v[144:147], v189
	ds_read_b128 v[148:151], v189 offset:1024
	ds_read_b128 v[168:171], v189 offset:2048
	ds_read_b128 v[172:175], v189 offset:3072
	ds_read_b128 v[176:179], v189 offset:4096
	ds_read_b128 v[180:183], v189 offset:5120
	ds_read_b128 v[194:197], v189 offset:6144
	ds_read_b128 v[198:201], v189 offset:7168
	global_load_lds_dwordx4 v[202:203], off
	v_lshl_add_u64 v[202:203], s[6:7], 0, v[162:163]
	s_add_i32 m0, s29, 0xe000
	s_nop 0
	global_load_lds_dwordx4 v[202:203], off
	s_waitcnt lgkmcnt(8)
	s_barrier
	s_waitcnt lgkmcnt(0)
	s_setprio 1
	s_waitcnt lgkmcnt(0)
	v_mfma_f32_16x16x32_bf16 v[124:127], v[128:131], v[144:147], v[124:127]
	v_mfma_f32_16x16x32_bf16 v[120:123], v[136:139], v[144:147], v[120:123]
	v_mfma_f32_16x16x32_bf16 v[116:119], v[128:131], v[168:171], v[116:119]
	v_mfma_f32_16x16x32_bf16 v[112:115], v[136:139], v[168:171], v[112:115]
	v_mfma_f32_16x16x32_bf16 v[108:111], v[128:131], v[176:179], v[108:111]
	v_mfma_f32_16x16x32_bf16 v[104:107], v[136:139], v[176:179], v[104:107]
	v_mfma_f32_16x16x32_bf16 v[100:103], v[128:131], v[194:197], v[100:103]
	v_mfma_f32_16x16x32_bf16 v[96:99], v[136:139], v[194:197], v[96:99]
	v_mfma_f32_16x16x32_bf16 v[124:127], v[132:135], v[148:151], v[124:127]
	v_mfma_f32_16x16x32_bf16 v[120:123], v[140:143], v[148:151], v[120:123]
	v_mfma_f32_16x16x32_bf16 v[116:119], v[132:135], v[172:175], v[116:119]
	v_mfma_f32_16x16x32_bf16 v[112:115], v[140:143], v[172:175], v[112:115]
	v_mfma_f32_16x16x32_bf16 v[108:111], v[132:135], v[180:183], v[108:111]
	v_mfma_f32_16x16x32_bf16 v[104:107], v[140:143], v[180:183], v[104:107]
	v_mfma_f32_16x16x32_bf16 v[100:103], v[132:135], v[198:201], v[100:103]
	v_mfma_f32_16x16x32_bf16 v[96:99], v[140:143], v[198:201], v[96:99]
	s_setprio 0
	s_barrier
	s_add_i32 s52, s47, s38
	v_lshl_add_u64 v[218:219], s[30:31], 0, v[156:157]
	s_mov_b32 m0, s52
	ds_read_b128 v[202:205], v190
	ds_read_b128 v[206:209], v190 offset:1024
	ds_read_b128 v[210:213], v190 offset:2048
	ds_read_b128 v[214:217], v190 offset:3072
	global_load_lds_dwordx4 v[218:219], off
	v_lshl_add_u64 v[220:221], s[30:31], 0, v[152:153]
	s_add_i32 m0, s52, 0x2000
	s_nop 0
	global_load_lds_dwordx4 v[220:221], off
	s_barrier
	s_waitcnt lgkmcnt(0)
	s_setprio 1
	s_waitcnt lgkmcnt(0)
	v_mfma_f32_16x16x32_bf16 v[60:63], v[202:205], v[144:147], v[60:63]
	v_mfma_f32_16x16x32_bf16 v[56:59], v[210:213], v[144:147], v[56:59]
	v_mfma_f32_16x16x32_bf16 v[52:55], v[202:205], v[168:171], v[52:55]
	v_mfma_f32_16x16x32_bf16 v[48:51], v[210:213], v[168:171], v[48:51]
	v_mfma_f32_16x16x32_bf16 v[44:47], v[202:205], v[176:179], v[44:47]
	v_mfma_f32_16x16x32_bf16 v[40:43], v[210:213], v[176:179], v[40:43]
	v_mfma_f32_16x16x32_bf16 v[36:39], v[202:205], v[194:197], v[36:39]
	v_mfma_f32_16x16x32_bf16 v[32:35], v[210:213], v[194:197], v[32:35]
	v_mfma_f32_16x16x32_bf16 v[60:63], v[206:209], v[148:151], v[60:63]
	v_mfma_f32_16x16x32_bf16 v[56:59], v[214:217], v[148:151], v[56:59]
	v_mfma_f32_16x16x32_bf16 v[52:55], v[206:209], v[172:175], v[52:55]
	v_mfma_f32_16x16x32_bf16 v[48:51], v[214:217], v[172:175], v[48:51]
	v_mfma_f32_16x16x32_bf16 v[44:47], v[206:209], v[180:183], v[44:47]
	v_mfma_f32_16x16x32_bf16 v[40:43], v[214:217], v[180:183], v[40:43]
	v_mfma_f32_16x16x32_bf16 v[36:39], v[206:209], v[198:201], v[36:39]
	v_mfma_f32_16x16x32_bf16 v[32:35], v[214:217], v[198:201], v[32:35]
	s_setprio 0
	s_mov_b32 m0, s29
	v_lshl_add_u64 v[222:223], s[34:35], 0, v[158:159]
	s_barrier
	ds_read_b128 v[144:147], v189 offset:16384
	ds_read_b128 v[148:151], v189 offset:17408
	ds_read_b128 v[168:171], v189 offset:18432
	ds_read_b128 v[172:175], v189 offset:19456
	ds_read_b128 v[176:179], v189 offset:20480
	ds_read_b128 v[180:183], v189 offset:21504
	ds_read_b128 v[194:197], v189 offset:22528
	ds_read_b128 v[198:201], v189 offset:23552
	global_load_lds_dwordx4 v[222:223], off
	v_lshl_add_u64 v[224:225], s[34:35], 0, v[154:155]
	s_mov_b32 m0, s39
	s_nop 0
	global_load_lds_dwordx4 v[224:225], off
	s_barrier
	s_waitcnt lgkmcnt(0)
	s_setprio 1
	s_waitcnt lgkmcnt(0)
	v_mfma_f32_16x16x32_bf16 v[92:95], v[128:131], v[144:147], v[92:95]
	v_mfma_f32_16x16x32_bf16 v[88:91], v[136:139], v[144:147], v[88:91]
	v_mfma_f32_16x16x32_bf16 v[84:87], v[128:131], v[168:171], v[84:87]
	v_mfma_f32_16x16x32_bf16 v[80:83], v[136:139], v[168:171], v[80:83]
	v_mfma_f32_16x16x32_bf16 v[76:79], v[128:131], v[176:179], v[76:79]
	v_mfma_f32_16x16x32_bf16 v[72:75], v[136:139], v[176:179], v[72:75]
	v_mfma_f32_16x16x32_bf16 v[68:71], v[128:131], v[194:197], v[68:71]
	v_mfma_f32_16x16x32_bf16 v[64:67], v[136:139], v[194:197], v[64:67]
	v_mfma_f32_16x16x32_bf16 v[92:95], v[132:135], v[148:151], v[92:95]
	v_mfma_f32_16x16x32_bf16 v[88:91], v[140:143], v[148:151], v[88:91]
	v_mfma_f32_16x16x32_bf16 v[84:87], v[132:135], v[172:175], v[84:87]
	v_mfma_f32_16x16x32_bf16 v[80:83], v[140:143], v[172:175], v[80:83]
	v_mfma_f32_16x16x32_bf16 v[76:79], v[132:135], v[180:183], v[76:79]
	v_mfma_f32_16x16x32_bf16 v[72:75], v[140:143], v[180:183], v[72:75]
	v_mfma_f32_16x16x32_bf16 v[68:71], v[132:135], v[198:201], v[68:71]
	v_mfma_f32_16x16x32_bf16 v[64:67], v[140:143], v[198:201], v[64:67]
	s_setprio 0
	s_barrier
	s_add_u32 s52, s30, 0x20000
	s_addc_u32 s53, s31, 0
	s_add_i32 s54, s48, s38
	v_lshl_add_u64 v[128:129], s[52:53], 0, v[156:157]
	s_mov_b32 m0, s54
	s_nop 0
	global_load_lds_dwordx4 v[128:129], off
	v_lshl_add_u64 v[128:129], s[52:53], 0, v[152:153]
	s_add_i32 m0, s54, 0x2000
	s_nop 0
	global_load_lds_dwordx4 v[128:129], off
	s_waitcnt vmcnt(6)
	s_barrier
	s_setprio 1
	v_mfma_f32_16x16x32_bf16 v[28:31], v[202:205], v[144:147], v[28:31]
	v_mfma_f32_16x16x32_bf16 v[24:27], v[210:213], v[144:147], v[24:27]
	v_mfma_f32_16x16x32_bf16 v[20:23], v[202:205], v[168:171], v[20:23]
	v_mfma_f32_16x16x32_bf16 v[16:19], v[210:213], v[168:171], v[16:19]
	v_mfma_f32_16x16x32_bf16 v[12:15], v[202:205], v[176:179], v[12:15]
	v_mfma_f32_16x16x32_bf16 v[8:11], v[210:213], v[176:179], v[8:11]
	v_mfma_f32_16x16x32_bf16 v[4:7], v[202:205], v[194:197], v[4:7]
	v_mfma_f32_16x16x32_bf16 v[0:3], v[210:213], v[194:197], v[0:3]
	v_mfma_f32_16x16x32_bf16 v[28:31], v[206:209], v[148:151], v[28:31]
	v_mfma_f32_16x16x32_bf16 v[24:27], v[214:217], v[148:151], v[24:27]
	v_mfma_f32_16x16x32_bf16 v[20:23], v[206:209], v[172:175], v[20:23]
	v_mfma_f32_16x16x32_bf16 v[16:19], v[214:217], v[172:175], v[16:19]
	v_mfma_f32_16x16x32_bf16 v[12:15], v[206:209], v[180:183], v[12:15]
	v_mfma_f32_16x16x32_bf16 v[8:11], v[214:217], v[180:183], v[8:11]
	v_mfma_f32_16x16x32_bf16 v[4:7], v[206:209], v[198:201], v[4:7]
	v_mfma_f32_16x16x32_bf16 v[0:3], v[214:217], v[198:201], v[0:3]
	s_setprio 0
	s_add_i32 s52, 0, 0x18000
	v_add_u32_e32 v140, s52, v186
	s_barrier
	ds_read_b128 v[128:131], v140
	ds_read_b128 v[132:135], v140 offset:1024
	ds_read_b128 v[136:139], v140 offset:2048
	ds_read_b128 v[140:143], v140 offset:3072
	s_add_u32 s34, s34, 0x80000
	s_addc_u32 s35, s35, 0
	s_mov_b32 m0, s40
	v_lshl_add_u64 v[202:203], s[34:35], 0, v[158:159]
	ds_read_b128 v[144:147], v189 offset:32768
	ds_read_b128 v[148:151], v189 offset:33792
	ds_read_b128 v[168:171], v189 offset:34816
	ds_read_b128 v[172:175], v189 offset:35840
	ds_read_b128 v[176:179], v189 offset:36864
	ds_read_b128 v[180:183], v189 offset:37888
	ds_read_b128 v[194:197], v189 offset:38912
	ds_read_b128 v[198:201], v189 offset:39936
	global_load_lds_dwordx4 v[202:203], off
	v_lshl_add_u64 v[202:203], s[34:35], 0, v[154:155]
	s_mov_b32 m0, s41
	s_nop 0
	global_load_lds_dwordx4 v[202:203], off
	s_waitcnt lgkmcnt(8)
	s_barrier
	s_waitcnt lgkmcnt(0)
	s_setprio 1
	s_waitcnt lgkmcnt(0)
	v_mfma_f32_16x16x32_bf16 v[124:127], v[128:131], v[144:147], v[124:127]
	v_mfma_f32_16x16x32_bf16 v[120:123], v[136:139], v[144:147], v[120:123]
	v_mfma_f32_16x16x32_bf16 v[116:119], v[128:131], v[168:171], v[116:119]
	v_mfma_f32_16x16x32_bf16 v[112:115], v[136:139], v[168:171], v[112:115]
	v_mfma_f32_16x16x32_bf16 v[108:111], v[128:131], v[176:179], v[108:111]
	v_mfma_f32_16x16x32_bf16 v[104:107], v[136:139], v[176:179], v[104:107]
	v_mfma_f32_16x16x32_bf16 v[100:103], v[128:131], v[194:197], v[100:103]
	v_mfma_f32_16x16x32_bf16 v[96:99], v[136:139], v[194:197], v[96:99]
	v_mfma_f32_16x16x32_bf16 v[124:127], v[132:135], v[148:151], v[124:127]
	v_mfma_f32_16x16x32_bf16 v[120:123], v[140:143], v[148:151], v[120:123]
	v_mfma_f32_16x16x32_bf16 v[116:119], v[132:135], v[172:175], v[116:119]
	v_mfma_f32_16x16x32_bf16 v[112:115], v[140:143], v[172:175], v[112:115]
	v_mfma_f32_16x16x32_bf16 v[108:111], v[132:135], v[180:183], v[108:111]
	v_mfma_f32_16x16x32_bf16 v[104:107], v[140:143], v[180:183], v[104:107]
	v_mfma_f32_16x16x32_bf16 v[100:103], v[132:135], v[198:201], v[100:103]
	v_mfma_f32_16x16x32_bf16 v[96:99], v[140:143], v[198:201], v[96:99]
	s_setprio 0
	s_barrier
	s_add_i32 s34, 0, 0x1c000
	s_add_i32 s35, s52, s38
	v_add_u32_e32 v191, s34, v186
	v_lshl_add_u64 v[218:219], v[218:219], 0, s[0:1]
	s_mov_b32 m0, s35
	ds_read_b128 v[202:205], v191
	ds_read_b128 v[206:209], v191 offset:1024
	ds_read_b128 v[210:213], v191 offset:2048
	ds_read_b128 v[214:217], v191 offset:3072
	global_load_lds_dwordx4 v[218:219], off
	v_lshl_add_u64 v[218:219], v[220:221], 0, s[0:1]
	s_add_i32 m0, s35, 0x2000
	s_nop 0
	global_load_lds_dwordx4 v[218:219], off
	s_barrier
	s_waitcnt lgkmcnt(0)
	s_setprio 1
	s_waitcnt lgkmcnt(0)
	v_mfma_f32_16x16x32_bf16 v[60:63], v[202:205], v[144:147], v[60:63]
	v_mfma_f32_16x16x32_bf16 v[56:59], v[210:213], v[144:147], v[56:59]
	v_mfma_f32_16x16x32_bf16 v[52:55], v[202:205], v[168:171], v[52:55]
	v_mfma_f32_16x16x32_bf16 v[48:51], v[210:213], v[168:171], v[48:51]
	v_mfma_f32_16x16x32_bf16 v[44:47], v[202:205], v[176:179], v[44:47]
	v_mfma_f32_16x16x32_bf16 v[40:43], v[210:213], v[176:179], v[40:43]
	v_mfma_f32_16x16x32_bf16 v[36:39], v[202:205], v[194:197], v[36:39]
	v_mfma_f32_16x16x32_bf16 v[32:35], v[210:213], v[194:197], v[32:35]
	v_mfma_f32_16x16x32_bf16 v[60:63], v[206:209], v[148:151], v[60:63]
	v_mfma_f32_16x16x32_bf16 v[56:59], v[214:217], v[148:151], v[56:59]
	v_mfma_f32_16x16x32_bf16 v[52:55], v[206:209], v[172:175], v[52:55]
	v_mfma_f32_16x16x32_bf16 v[48:51], v[214:217], v[172:175], v[48:51]
	v_mfma_f32_16x16x32_bf16 v[44:47], v[206:209], v[180:183], v[44:47]
	v_mfma_f32_16x16x32_bf16 v[40:43], v[214:217], v[180:183], v[40:43]
	v_mfma_f32_16x16x32_bf16 v[36:39], v[206:209], v[198:201], v[36:39]
	v_mfma_f32_16x16x32_bf16 v[32:35], v[214:217], v[198:201], v[32:35]
	s_setprio 0
	s_mov_b32 m0, s43
	v_lshl_add_u64 v[218:219], v[222:223], 0, s[0:1]
	s_barrier
	ds_read_b128 v[144:147], v189 offset:49152
	ds_read_b128 v[148:151], v189 offset:50176
	ds_read_b128 v[168:171], v189 offset:51200
	ds_read_b128 v[172:175], v189 offset:52224
	ds_read_b128 v[176:179], v189 offset:53248
	ds_read_b128 v[180:183], v189 offset:54272
	ds_read_b128 v[194:197], v189 offset:55296
	ds_read_b128 v[198:201], v189 offset:56320
	global_load_lds_dwordx4 v[218:219], off
	v_lshl_add_u64 v[218:219], v[224:225], 0, s[0:1]
	s_mov_b32 m0, s44
	s_nop 0
	global_load_lds_dwordx4 v[218:219], off
	s_barrier
; template <class Epi>
; __device__ __forceinline__ void gemm_phase(LAS unsigned char* lds, const GemmD g, const Epi& E) {
;     ...
;         for (int t = 0; t < nt; t += 2) PG8_KITER(t);
;     __device__ __forceinline__ void operator()(const f32x4 (&acc)[2][2][4][2], const Unit& u, int wr, int wc, int fr, int fq) const {
;         const int row0 = u.pm * BM + wr * 64 + fr, col0 = u.pn * BM + wc * 32 + 8 * fq;
; #pragma unroll
;         for (int bj = 0; bj < 2; ++bj) { const int col = col0 + bj * HALF;
;             const f32x4 b0 = *(const f32x4*)(bias + col), b1 = *(const f32x4*)(bias + col + 4), s0 = *(const f32x4*)(scale + col), s1 = *(const f32x4*)(scale + col + 4);
; #pragma unroll
;             for (int ai = 0; ai < 2; ++ai)
; #pragma unroll
;                 for (int m = 0; m < 4; ++m) { const int row = row0 + ai * HALF + m * 16;
;                     const u32x4 z = __builtin_nontemporal_load((const u32x4*)(proj + (size_t)row * NPROJ + C_ZP + col));
	s_waitcnt lgkmcnt(0)
	s_setprio 1
	s_waitcnt lgkmcnt(0)
	v_mfma_f32_16x16x32_bf16 v[92:95], v[128:131], v[144:147], v[92:95]
	v_mfma_f32_16x16x32_bf16 v[88:91], v[136:139], v[144:147], v[88:91]
	v_mfma_f32_16x16x32_bf16 v[84:87], v[128:131], v[168:171], v[84:87]
	v_mfma_f32_16x16x32_bf16 v[80:83], v[136:139], v[168:171], v[80:83]
	v_mfma_f32_16x16x32_bf16 v[76:79], v[128:131], v[176:179], v[76:79]
	v_mfma_f32_16x16x32_bf16 v[72:75], v[136:139], v[176:179], v[72:75]
	v_mfma_f32_16x16x32_bf16 v[68:71], v[128:131], v[194:197], v[68:71]
	v_mfma_f32_16x16x32_bf16 v[64:67], v[136:139], v[194:197], v[64:67]
	v_mfma_f32_16x16x32_bf16 v[92:95], v[132:135], v[148:151], v[92:95]
	v_mfma_f32_16x16x32_bf16 v[88:91], v[140:143], v[148:151], v[88:91]
	v_mfma_f32_16x16x32_bf16 v[84:87], v[132:135], v[172:175], v[84:87]
	v_mfma_f32_16x16x32_bf16 v[80:83], v[140:143], v[172:175], v[80:83]
	v_mfma_f32_16x16x32_bf16 v[76:79], v[132:135], v[180:183], v[76:79]
	v_mfma_f32_16x16x32_bf16 v[72:75], v[140:143], v[180:183], v[72:75]
	v_mfma_f32_16x16x32_bf16 v[68:71], v[132:135], v[198:201], v[68:71]
	v_mfma_f32_16x16x32_bf16 v[64:67], v[140:143], v[198:201], v[64:67]
	s_setprio 0
	s_barrier
	s_add_u32 s30, s30, 0x20080
	s_addc_u32 s31, s31, 0
	s_add_i32 s34, s34, s38
	v_lshl_add_u64 v[128:129], s[30:31], 0, v[156:157]
	s_mov_b32 m0, s34
	s_nop 0
	global_load_lds_dwordx4 v[128:129], off
	v_lshl_add_u64 v[128:129], s[30:31], 0, v[152:153]
	s_add_i32 m0, s34, 0x2000
	s_nop 0
	global_load_lds_dwordx4 v[128:129], off
	s_waitcnt vmcnt(6)
	s_barrier
	s_setprio 1
	v_mfma_f32_16x16x32_bf16 v[28:31], v[202:205], v[144:147], v[28:31]
	v_mfma_f32_16x16x32_bf16 v[24:27], v[210:213], v[144:147], v[24:27]
	v_mfma_f32_16x16x32_bf16 v[20:23], v[202:205], v[168:171], v[20:23]
	v_mfma_f32_16x16x32_bf16 v[16:19], v[210:213], v[168:171], v[16:19]
	v_mfma_f32_16x16x32_bf16 v[12:15], v[202:205], v[176:179], v[12:15]
	v_mfma_f32_16x16x32_bf16 v[8:11], v[210:213], v[176:179], v[8:11]
	v_mfma_f32_16x16x32_bf16 v[4:7], v[202:205], v[194:197], v[4:7]
	v_mfma_f32_16x16x32_bf16 v[0:3], v[210:213], v[194:197], v[0:3]
	v_mfma_f32_16x16x32_bf16 v[28:31], v[206:209], v[148:151], v[28:31]
	v_mfma_f32_16x16x32_bf16 v[24:27], v[214:217], v[148:151], v[24:27]
	v_mfma_f32_16x16x32_bf16 v[20:23], v[206:209], v[172:175], v[20:23]
	v_mfma_f32_16x16x32_bf16 v[16:19], v[214:217], v[172:175], v[16:19]
	v_mfma_f32_16x16x32_bf16 v[12:15], v[206:209], v[180:183], v[12:15]
	v_mfma_f32_16x16x32_bf16 v[8:11], v[214:217], v[180:183], v[8:11]
	v_mfma_f32_16x16x32_bf16 v[4:7], v[206:209], v[198:201], v[4:7]
	v_mfma_f32_16x16x32_bf16 v[0:3], v[214:217], v[198:201], v[0:3]
	s_setprio 0
	s_add_i32 s51, s51, 2
	s_add_u32 s6, s6, 0x100
	s_addc_u32 s7, s7, 0
	s_add_u32 s13, s13, 0x100
	s_addc_u32 s15, s15, 0
	s_cmp_gt_u32 s51, 5
	s_barrier
	s_cbranch_scc0 .LBB0_600
	v_lshl_add_u32 v176, s28, 8, v185
	v_lshl_or_b32 v148, s50, 8, v187
	v_mov_b64_e32 v[178:179], s[92:93]
	v_ashrrev_i32_e32 v149, 31, v148
	v_readlane_b32 s52, v244, 0
	v_mad_i64_i32 v[138:139], s[2:3], v176, s49, v[178:179]
	v_lshlrev_b64 v[136:137], 2, v[148:149]
	v_readlane_b32 s53, v244, 1
	v_lshl_add_u64 v[150:151], v[138:139], 0, s[8:9]
	v_lshlrev_b64 v[174:175], 1, v[148:149]
	v_lshl_add_u64 v[170:171], s[52:53], 0, v[136:137]
	v_lshl_add_u64 v[138:139], v[150:151], 0, v[174:175]
	global_load_dwordx4 v[128:131], v[170:171], off offset:16
	global_load_dwordx4 v[132:135], v[170:171], off
	v_mov_b32_e32 v254, v138
	v_mov_b32_e32 v255, v139
	global_load_dwordx4 v[144:147], v[138:139], off nt
	v_readlane_b32 s54, v244, 2
	v_readlane_b32 s55, v244, 3
	v_ashrrev_i32_e32 v177, 31, v176
	v_lshlrev_b64 v[168:169], 13, v[176:177]
	v_lshl_add_u64 v[172:173], s[54:55], 0, v[136:137]
	global_load_dwordx4 v[140:143], v[172:173], off
	global_load_dwordx4 v[136:139], v[172:173], off offset:16
	v_readlane_b32 s6, v244, 45
	v_readlane_b32 s7, v244, 46
	v_or_b32_e32 v182, 16, v176
	v_mad_i64_i32 v[194:195], s[2:3], v182, s49, v[178:179]
	v_lshl_add_u64 v[180:181], s[6:7], 0, v[168:169]
	v_lshl_add_u64 v[180:181], v[180:181], 0, s[10:11]
	v_lshl_add_u64 v[196:197], v[180:181], 0, v[174:175]
	v_or_b32_e32 v148, 0x80, v148
	v_ashrrev_i32_e32 v149, 31, v148
	v_lshlrev_b64 v[168:169], 1, v[148:149]
	v_lshl_add_u64 v[148:149], v[150:151], 0, v[168:169]
	global_load_dwordx4 v[148:151], v[148:149], off nt
	global_load_dwordx4 v[234:237], v[170:171], off offset:512
	global_load_dwordx4 v[238:241], v[170:171], off offset:528
	global_load_dwordx4 v[246:249], v[172:173], off offset:512
	global_load_dwordx4 v[250:253], v[172:173], off offset:528
	s_mov_b32 s60, 0x6a000
	s_mov_b32 s61, 0
	v_lshl_add_u64 v[206:207], v[254:255], 0, s[60:61]
	global_load_dwordx4 v[206:209], v[206:207], off nt
	s_mov_b32 s60, 0xd4000
	s_mov_b32 s61, 0
	v_lshl_add_u64 v[210:211], v[254:255], 0, s[60:61]
	global_load_dwordx4 v[210:213], v[210:211], off nt
	s_mov_b32 s60, 0x13e000
	s_mov_b32 s61, 0
	v_lshl_add_u64 v[214:215], v[254:255], 0, s[60:61]
	global_load_dwordx4 v[214:217], v[214:215], off nt
	s_mov_b32 s60, 0x350000
	s_mov_b32 s61, 0
	v_lshl_add_u64 v[218:219], v[254:255], 0, s[60:61]
	global_load_dwordx4 v[218:221], v[218:219], off nt
	s_mov_b32 s60, 0x3ba000
	s_mov_b32 s61, 0
	v_lshl_add_u64 v[222:223], v[254:255], 0, s[60:61]
	global_load_dwordx4 v[222:225], v[222:223], off nt
	s_mov_b32 s60, 0x424000
	s_mov_b32 s61, 0
	v_lshl_add_u64 v[226:227], v[254:255], 0, s[60:61]
	global_load_dwordx4 v[226:229], v[226:227], off nt
	s_mov_b32 s60, 0x48e000
	s_mov_b32 s61, 0
	v_lshl_add_u64 v[230:231], v[254:255], 0, s[60:61]
	global_load_dwordx4 v[230:233], v[230:231], off nt
	s_and_b64 vcc, exec, s[4:5]
	s_mov_b32 s50, s12
	s_mov_b32 s28, s14
	s_mov_b64 s[30:31], s[26:27]
	s_mov_b64 s[34:35], s[24:25]
	v_readlane_b32 s56, v244, 4
	v_readlane_b32 s57, v244, 5
	v_readlane_b32 s58, v244, 6
	v_readlane_b32 s59, v244, 7
	s_waitcnt vmcnt(12)
; __device__ __forceinline__ float bflo(unsigned w) { return __uint_as_float(w << 16); }
; __device__ __forceinline__ float bfhi(unsigned w) { return __uint_as_float(w & 0xffff0000u); }
; __device__ __forceinline__ unsigned pk2(float lo, float hi) { unsigned r; asm("v_cvt_pk_bf16_f32 %0, %1, %2" : "=v"(r) : "v"(lo), "v"(hi)); return r; }
; __device__ __forceinline__ float siluf_(float x) { return x * __builtin_amdgcn_rcpf(1.0f + __expf(-x)); }
;     __device__ __forceinline__ void operator()(const f32x4 (&acc)[2][2][4][2], const Unit& u, int wr, int wc, int fr, int fq) const {
;     ...
;         for (int bj = 0; bj < 2; ++bj) { const int col = col0 + bj * HALF;
;             const f32x4 b0 = *(const f32x4*)(bias + col), b1 = *(const f32x4*)(bias + col + 4), s0 = *(const f32x4*)(scale + col), s1 = *(const f32x4*)(scale + col + 4);
; #pragma unroll
;             for (int ai = 0; ai < 2; ++ai)
; #pragma unroll
;                 for (int m = 0; m < 4; ++m) { const int row = row0 + ai * HALF + m * 16;
;                     const u32x4 z = __builtin_nontemporal_load((const u32x4*)(proj + (size_t)row * NPROJ + C_ZP + col));
;                     f32x4 v0 = (acc[ai][bj][m][0] + b0) * s0, v1 = (acc[ai][bj][m][1] + b1) * s1;
;                     v0[0] *= siluf_(bflo(z.x)); v0[1] *= siluf_(bfhi(z.x)); v0[2] *= siluf_(bflo(z.y)); v0[3] *= siluf_(bfhi(z.y));
;                     v1[0] *= siluf_(bflo(z.z)); v1[1] *= siluf_(bfhi(z.z)); v1[2] *= siluf_(bflo(z.w)); v1[3] *= siluf_(bfhi(z.w));
;                     u32x4 w; w.x = pk2(v0[0], v0[1]); w.y = pk2(v0[2], v0[3]); w.z = pk2(v1[0], v1[1]); w.w = pk2(v1[2], v1[3]);
;                     *(u32x4*)(a2 + (size_t)row * 4096 + 2048 + col) = w; } }
	v_pk_add_f32 v[122:123], v[122:123], v[130:131]
	v_pk_add_f32 v[124:125], v[124:125], v[132:133]
	v_lshlrev_b32_e32 v177, 16, v144
	v_and_b32_e32 v144, 0xffff0000, v144
	v_lshlrev_b32_e32 v183, 16, v145
	v_and_b32_e32 v145, 0xffff0000, v145
	v_lshlrev_b32_e32 v191, 16, v146
	v_and_b32_e32 v146, 0xffff0000, v146
	v_lshlrev_b32_e32 v193, 16, v147
	v_and_b32_e32 v147, 0xffff0000, v147
	v_mul_f32_e32 v198, 0xbfb8aa3b, v177
	v_mul_f32_e32 v199, 0xbfb8aa3b, v144
	v_mul_f32_e32 v200, 0xbfb8aa3b, v183
	v_mul_f32_e32 v201, 0xbfb8aa3b, v145
	v_mul_f32_e32 v202, 0xbfb8aa3b, v191
	v_mul_f32_e32 v203, 0xbfb8aa3b, v146
	v_mul_f32_e32 v205, 0xbfb8aa3b, v147
	v_exp_f32_e32 v198, v198
	v_exp_f32_e32 v199, v199
	v_mul_f32_e32 v204, 0xbfb8aa3b, v193
	v_exp_f32_e32 v200, v200
	v_exp_f32_e32 v201, v201
	v_exp_f32_e32 v202, v202
	v_exp_f32_e32 v203, v203
	v_exp_f32_e32 v205, v205
	v_exp_f32_e32 v204, v204
	v_add_f32_e32 v198, 1.0, v198
	v_add_f32_e32 v199, 1.0, v199
	v_add_f32_e32 v200, 1.0, v200
	v_add_f32_e32 v201, 1.0, v201
	v_add_f32_e32 v202, 1.0, v202
	v_add_f32_e32 v203, 1.0, v203
	v_add_f32_e32 v205, 1.0, v205
	v_rcp_f32_e32 v198, v198
	v_rcp_f32_e32 v199, v199
	v_add_f32_e32 v204, 1.0, v204
	v_rcp_f32_e32 v200, v200
	v_rcp_f32_e32 v201, v201
	v_rcp_f32_e32 v202, v202
	v_rcp_f32_e32 v203, v203
	v_rcp_f32_e32 v205, v205
	v_rcp_f32_e32 v204, v204
	v_pk_add_f32 v[126:127], v[126:127], v[134:135]
	v_pk_add_f32 v[120:121], v[120:121], v[128:129]
	v_pk_mul_f32 v[124:125], v[124:125], v[140:141]
	v_mul_f32_e32 v177, v198, v177
	v_mul_f32_e32 v144, v199, v144
	v_pk_mul_f32 v[126:127], v[126:127], v[142:143]
	v_pk_mul_f32 v[122:123], v[122:123], v[138:139]
	v_pk_mul_f32 v[120:121], v[120:121], v[136:137]
	v_mul_f32_e32 v183, v200, v183
	v_mul_f32_e32 v145, v201, v145
	v_mul_f32_e32 v191, v202, v191
	v_mul_f32_e32 v146, v203, v146
	v_mul_f32_e32 v147, v205, v147
	v_mul_f32_e32 v124, v124, v177
	v_mul_f32_e32 v125, v125, v144
	v_mul_f32_e32 v193, v204, v193
	v_mul_f32_e32 v126, v126, v183
	v_mul_f32_e32 v127, v127, v145
	v_mul_f32_e32 v144, v120, v191
	v_mul_f32_e32 v145, v121, v146
	v_mul_f32_e32 v123, v123, v147
	v_cvt_pk_bf16_f32 v120, v124, v125
	v_cvt_pk_bf16_f32 v121, v126, v127
	v_lshl_add_u64 v[124:125], v[194:195], 0, s[8:9]
	v_mul_f32_e32 v146, v122, v193
	v_cvt_pk_bf16_f32 v122, v144, v145
	v_cvt_pk_bf16_f32 v123, v146, v123
	global_store_dwordx4 v[196:197], v[120:123], off
	v_ashrrev_i32_e32 v183, 31, v182
	v_or_b32_e32 v126, 32, v176
	v_lshl_add_u64 v[120:121], v[124:125], 0, v[174:175]
	v_lshlrev_b64 v[122:123], 13, v[182:183]
	v_lshl_add_u64 v[122:123], s[6:7], 0, v[122:123]
	v_pk_add_f32 v[114:115], v[114:115], v[130:131]
	v_mad_i64_i32 v[120:121], s[2:3], v126, s49, v[178:179]
	v_lshl_add_u64 v[122:123], v[122:123], 0, s[10:11]
	v_pk_add_f32 v[118:119], v[118:119], v[134:135]
	v_pk_add_f32 v[116:117], v[116:117], v[132:133]
	v_pk_add_f32 v[112:113], v[112:113], v[128:129]
	v_pk_mul_f32 v[114:115], v[114:115], v[138:139]
	v_lshl_add_u64 v[120:121], v[120:121], 0, s[8:9]
	v_lshl_add_u64 v[194:195], v[122:123], 0, v[174:175]
	v_pk_mul_f32 v[118:119], v[118:119], v[142:143]
	v_pk_mul_f32 v[116:117], v[116:117], v[140:141]
	v_pk_mul_f32 v[112:113], v[112:113], v[136:137]
	v_lshl_add_u64 v[182:183], v[120:121], 0, v[174:175]
	v_pk_add_f32 v[106:107], v[106:107], v[130:131]
	v_pk_add_f32 v[110:111], v[110:111], v[134:135]
	v_pk_add_f32 v[108:109], v[108:109], v[132:133]
	v_pk_add_f32 v[104:105], v[104:105], v[128:129]
	v_pk_mul_f32 v[106:107], v[106:107], v[138:139]
	v_pk_mul_f32 v[110:111], v[110:111], v[142:143]
	v_pk_mul_f32 v[108:109], v[108:109], v[140:141]
	v_pk_mul_f32 v[104:105], v[104:105], v[136:137]
	v_pk_add_f32 v[98:99], v[98:99], v[130:131]
	v_pk_add_f32 v[102:103], v[102:103], v[134:135]
	v_pk_add_f32 v[100:101], v[100:101], v[132:133]
	v_pk_add_f32 v[96:97], v[96:97], v[128:129]
	v_pk_mul_f32 v[98:99], v[98:99], v[138:139]
	v_pk_mul_f32 v[102:103], v[102:103], v[142:143]
	v_pk_mul_f32 v[100:101], v[100:101], v[140:141]
	v_pk_mul_f32 v[96:97], v[96:97], v[136:137]
	v_pk_add_f32 v[90:91], v[90:91], v[130:131]
	v_pk_add_f32 v[94:95], v[94:95], v[134:135]
	v_pk_add_f32 v[92:93], v[92:93], v[132:133]
	v_pk_add_f32 v[88:89], v[88:89], v[128:129]
	v_pk_mul_f32 v[90:91], v[90:91], v[138:139]
	v_pk_mul_f32 v[94:95], v[94:95], v[142:143]
	v_pk_mul_f32 v[92:93], v[92:93], v[140:141]
	v_pk_mul_f32 v[88:89], v[88:89], v[136:137]
	v_pk_add_f32 v[82:83], v[82:83], v[130:131]
	v_pk_add_f32 v[86:87], v[86:87], v[134:135]
	v_pk_add_f32 v[84:85], v[84:85], v[132:133]
	v_pk_add_f32 v[80:81], v[80:81], v[128:129]
	v_pk_mul_f32 v[82:83], v[82:83], v[138:139]
	v_pk_mul_f32 v[86:87], v[86:87], v[142:143]
	v_pk_mul_f32 v[84:85], v[84:85], v[140:141]
	v_pk_mul_f32 v[80:81], v[80:81], v[136:137]
	v_pk_add_f32 v[74:75], v[74:75], v[130:131]
	v_pk_add_f32 v[78:79], v[78:79], v[134:135]
	v_pk_add_f32 v[76:77], v[76:77], v[132:133]
	v_pk_add_f32 v[72:73], v[72:73], v[128:129]
	v_pk_mul_f32 v[74:75], v[74:75], v[138:139]
	v_pk_mul_f32 v[78:79], v[78:79], v[142:143]
	v_pk_mul_f32 v[76:77], v[76:77], v[140:141]
	v_pk_mul_f32 v[72:73], v[72:73], v[136:137]
	v_pk_add_f32 v[66:67], v[66:67], v[130:131]
	v_pk_add_f32 v[70:71], v[70:71], v[134:135]
	v_pk_add_f32 v[68:69], v[68:69], v[132:133]
	v_pk_add_f32 v[64:65], v[64:65], v[128:129]
	v_pk_mul_f32 v[66:67], v[66:67], v[138:139]
	v_pk_mul_f32 v[70:71], v[70:71], v[142:143]
	v_pk_mul_f32 v[68:69], v[68:69], v[140:141]
	v_pk_mul_f32 v[64:65], v[64:65], v[136:137]
	s_waitcnt vmcnt(7)
; __device__ __forceinline__ float bflo(unsigned w) { return __uint_as_float(w << 16); }
; __device__ __forceinline__ float bfhi(unsigned w) { return __uint_as_float(w & 0xffff0000u); }
; __device__ __forceinline__ unsigned pk2(float lo, float hi) { unsigned r; asm("v_cvt_pk_bf16_f32 %0, %1, %2" : "=v"(r) : "v"(lo), "v"(hi)); return r; }
; __device__ __forceinline__ float siluf_(float x) { return x * __builtin_amdgcn_rcpf(1.0f + __expf(-x)); }
;     __device__ __forceinline__ void operator()(const f32x4 (&acc)[2][2][4][2], const Unit& u, int wr, int wc, int fr, int fq) const {
;     ...
;             for (int ai = 0; ai < 2; ++ai)
; #pragma unroll
;                 for (int m = 0; m < 4; ++m) { const int row = row0 + ai * HALF + m * 16;
;                     const u32x4 z = __builtin_nontemporal_load((const u32x4*)(proj + (size_t)row * NPROJ + C_ZP + col));
;                     f32x4 v0 = (acc[ai][bj][m][0] + b0) * s0, v1 = (acc[ai][bj][m][1] + b1) * s1;
;                     v0[0] *= siluf_(bflo(z.x)); v0[1] *= siluf_(bfhi(z.x)); v0[2] *= siluf_(bflo(z.y)); v0[3] *= siluf_(bfhi(z.y));
;                     v1[0] *= siluf_(bflo(z.z)); v1[1] *= siluf_(bfhi(z.z)); v1[2] *= siluf_(bflo(z.w)); v1[3] *= siluf_(bfhi(z.w));
;                     u32x4 w; w.x = pk2(v0[0], v0[1]); w.y = pk2(v0[2], v0[3]); w.z = pk2(v1[0], v1[1]); w.w = pk2(v1[2], v1[3]);
;                     *(u32x4*)(a2 + (size_t)row * 4096 + 2048 + col) = w; } }
	v_mov_b32_e32 v144, v206
	v_mov_b32_e32 v145, v207
	v_mov_b32_e32 v146, v208
	v_mov_b32_e32 v147, v209
	s_mov_b32 s60, 0x6a100
	s_mov_b32 s61, 0
	v_lshl_add_u64 v[206:207], v[254:255], 0, s[60:61]
	global_load_dwordx4 v[206:209], v[206:207], off nt
	v_lshlrev_b32_e32 v193, 16, v147
	v_and_b32_e32 v147, 0xffff0000, v147
	v_lshlrev_b32_e32 v127, 16, v144
	v_and_b32_e32 v144, 0xffff0000, v144
	v_lshlrev_b32_e32 v177, 16, v145
	v_and_b32_e32 v145, 0xffff0000, v145
	v_lshlrev_b32_e32 v191, 16, v146
	v_and_b32_e32 v146, 0xffff0000, v146
	v_mul_f32_e32 v203, 0xbfb8aa3b, v147
	v_mul_f32_e32 v196, 0xbfb8aa3b, v127
	v_mul_f32_e32 v197, 0xbfb8aa3b, v144
	v_mul_f32_e32 v198, 0xbfb8aa3b, v177
	v_mul_f32_e32 v199, 0xbfb8aa3b, v145
	v_mul_f32_e32 v200, 0xbfb8aa3b, v191
	v_mul_f32_e32 v201, 0xbfb8aa3b, v146
	v_mul_f32_e32 v202, 0xbfb8aa3b, v193
	v_exp_f32_e32 v203, v203
	v_exp_f32_e32 v196, v196
	v_exp_f32_e32 v197, v197
	v_exp_f32_e32 v198, v198
	v_exp_f32_e32 v199, v199
	v_exp_f32_e32 v200, v200
	v_exp_f32_e32 v201, v201
	v_exp_f32_e32 v202, v202
	v_add_f32_e32 v203, 1.0, v203
	v_add_f32_e32 v196, 1.0, v196
	v_add_f32_e32 v197, 1.0, v197
	v_add_f32_e32 v198, 1.0, v198
	v_add_f32_e32 v199, 1.0, v199
	v_add_f32_e32 v200, 1.0, v200
	v_add_f32_e32 v201, 1.0, v201
	v_add_f32_e32 v202, 1.0, v202
	v_rcp_f32_e32 v203, v203
	v_rcp_f32_e32 v196, v196
	v_rcp_f32_e32 v197, v197
	v_rcp_f32_e32 v198, v198
	v_rcp_f32_e32 v199, v199
	v_rcp_f32_e32 v200, v200
	v_rcp_f32_e32 v201, v201
	v_rcp_f32_e32 v202, v202
	v_mul_f32_e32 v147, v203, v147
	v_mul_f32_e32 v127, v196, v127
	v_mul_f32_e32 v144, v197, v144
	v_mul_f32_e32 v177, v198, v177
	v_mul_f32_e32 v145, v199, v145
	v_mul_f32_e32 v191, v200, v191
	v_mul_f32_e32 v146, v201, v146
	v_mul_f32_e32 v193, v202, v193
	v_mul_f32_e32 v115, v115, v147
	v_mul_f32_e32 v116, v116, v127
	v_mul_f32_e32 v117, v117, v144
	v_mul_f32_e32 v118, v118, v177
	v_mul_f32_e32 v119, v119, v145
	v_mul_f32_e32 v127, v112, v191
	v_mul_f32_e32 v144, v113, v146
	v_mul_f32_e32 v145, v114, v193
	v_cvt_pk_bf16_f32 v112, v116, v117
	v_cvt_pk_bf16_f32 v113, v118, v119
	v_cvt_pk_bf16_f32 v114, v127, v144
	v_cvt_pk_bf16_f32 v115, v145, v115
	global_store_dwordx4 v[194:195], v[112:115], off
	v_ashrrev_i32_e32 v127, 31, v126
	v_lshlrev_b64 v[114:115], 13, v[126:127]
	v_or_b32_e32 v144, 48, v176
	v_lshl_add_u64 v[114:115], s[6:7], 0, v[114:115]
	v_mad_i64_i32 v[112:113], s[2:3], v144, s49, v[178:179]
	v_lshl_add_u64 v[114:115], v[114:115], 0, s[10:11]
	v_lshl_add_u64 v[112:113], v[112:113], 0, s[8:9]
	v_lshl_add_u64 v[146:147], v[114:115], 0, v[174:175]
	v_lshl_add_u64 v[126:127], v[112:113], 0, v[174:175]
	s_waitcnt vmcnt(8)
	v_mov_b32_e32 v116, v210
	v_mov_b32_e32 v117, v211
	v_mov_b32_e32 v118, v212
	v_mov_b32_e32 v119, v213
	s_mov_b32 s60, 0xd4100
	s_mov_b32 s61, 0
	v_lshl_add_u64 v[210:211], v[254:255], 0, s[60:61]
	global_load_dwordx4 v[210:213], v[210:211], off nt
	v_lshlrev_b32_e32 v183, 16, v119
	v_and_b32_e32 v119, 0xffff0000, v119
	v_lshlrev_b32_e32 v145, 16, v116
	v_and_b32_e32 v116, 0xffff0000, v116
	v_lshlrev_b32_e32 v177, 16, v117
	v_and_b32_e32 v117, 0xffff0000, v117
	v_lshlrev_b32_e32 v182, 16, v118
	v_and_b32_e32 v118, 0xffff0000, v118
	v_mul_f32_e32 v199, 0xbfb8aa3b, v119
	v_mul_f32_e32 v191, 0xbfb8aa3b, v145
	v_mul_f32_e32 v193, 0xbfb8aa3b, v116
	v_mul_f32_e32 v194, 0xbfb8aa3b, v177
	v_mul_f32_e32 v195, 0xbfb8aa3b, v117
	v_mul_f32_e32 v196, 0xbfb8aa3b, v182
	v_mul_f32_e32 v197, 0xbfb8aa3b, v118
	v_mul_f32_e32 v198, 0xbfb8aa3b, v183
	v_exp_f32_e32 v199, v199
	v_exp_f32_e32 v191, v191
	v_exp_f32_e32 v193, v193
	v_exp_f32_e32 v194, v194
	v_exp_f32_e32 v195, v195
	v_exp_f32_e32 v196, v196
	v_exp_f32_e32 v197, v197
	v_exp_f32_e32 v198, v198
	v_add_f32_e32 v199, 1.0, v199
	v_add_f32_e32 v191, 1.0, v191
	v_add_f32_e32 v193, 1.0, v193
	v_add_f32_e32 v194, 1.0, v194
	v_add_f32_e32 v195, 1.0, v195
	v_add_f32_e32 v196, 1.0, v196
	v_add_f32_e32 v197, 1.0, v197
	v_add_f32_e32 v198, 1.0, v198
	v_rcp_f32_e32 v199, v199
	v_rcp_f32_e32 v191, v191
	v_rcp_f32_e32 v193, v193
	v_rcp_f32_e32 v194, v194
	v_rcp_f32_e32 v195, v195
	v_rcp_f32_e32 v196, v196
	v_rcp_f32_e32 v197, v197
	v_rcp_f32_e32 v198, v198
	v_mul_f32_e32 v119, v199, v119
	v_mul_f32_e32 v145, v191, v145
	v_mul_f32_e32 v116, v193, v116
	v_mul_f32_e32 v177, v194, v177
	v_mul_f32_e32 v117, v195, v117
	v_mul_f32_e32 v182, v196, v182
	v_mul_f32_e32 v118, v197, v118
	v_mul_f32_e32 v183, v198, v183
	v_mul_f32_e32 v107, v107, v119
	v_mul_f32_e32 v108, v108, v145
	v_mul_f32_e32 v109, v109, v116
	v_mul_f32_e32 v110, v110, v177
	v_mul_f32_e32 v111, v111, v117
	v_mul_f32_e32 v116, v104, v182
	v_mul_f32_e32 v117, v105, v118
	v_mul_f32_e32 v118, v106, v183
	v_cvt_pk_bf16_f32 v104, v108, v109
	v_cvt_pk_bf16_f32 v105, v110, v111
	v_cvt_pk_bf16_f32 v106, v116, v117
	v_cvt_pk_bf16_f32 v107, v118, v107
	global_store_dwordx4 v[146:147], v[104:107], off
	v_ashrrev_i32_e32 v145, 31, v144
	v_lshlrev_b64 v[106:107], 13, v[144:145]
	v_add_u32_e32 v116, 0x80, v176
	v_lshl_add_u64 v[106:107], s[6:7], 0, v[106:107]
	v_mad_i64_i32 v[104:105], s[2:3], v116, s49, v[178:179]
	v_lshl_add_u64 v[106:107], v[106:107], 0, s[10:11]
	v_lshl_add_u64 v[104:105], v[104:105], 0, s[8:9]
	v_lshl_add_u64 v[126:127], v[106:107], 0, v[174:175]
	v_lshl_add_u64 v[118:119], v[104:105], 0, v[174:175]
	s_waitcnt vmcnt(9)
; __device__ __forceinline__ float bflo(unsigned w) { return __uint_as_float(w << 16); }
; __device__ __forceinline__ float bfhi(unsigned w) { return __uint_as_float(w & 0xffff0000u); }
; __device__ __forceinline__ unsigned pk2(float lo, float hi) { unsigned r; asm("v_cvt_pk_bf16_f32 %0, %1, %2" : "=v"(r) : "v"(lo), "v"(hi)); return r; }
; __device__ __forceinline__ float siluf_(float x) { return x * __builtin_amdgcn_rcpf(1.0f + __expf(-x)); }
;     __device__ __forceinline__ void operator()(const f32x4 (&acc)[2][2][4][2], const Unit& u, int wr, int wc, int fr, int fq) const {
;     ...
;             for (int ai = 0; ai < 2; ++ai)
; #pragma unroll
;                 for (int m = 0; m < 4; ++m) { const int row = row0 + ai * HALF + m * 16;
;                     const u32x4 z = __builtin_nontemporal_load((const u32x4*)(proj + (size_t)row * NPROJ + C_ZP + col));
;                     f32x4 v0 = (acc[ai][bj][m][0] + b0) * s0, v1 = (acc[ai][bj][m][1] + b1) * s1;
;                     v0[0] *= siluf_(bflo(z.x)); v0[1] *= siluf_(bfhi(z.x)); v0[2] *= siluf_(bflo(z.y)); v0[3] *= siluf_(bfhi(z.y));
;                     v1[0] *= siluf_(bflo(z.z)); v1[1] *= siluf_(bfhi(z.z)); v1[2] *= siluf_(bflo(z.w)); v1[3] *= siluf_(bfhi(z.w));
;                     u32x4 w; w.x = pk2(v0[0], v0[1]); w.y = pk2(v0[2], v0[3]); w.z = pk2(v1[0], v1[1]); w.w = pk2(v1[2], v1[3]);
;                     *(u32x4*)(a2 + (size_t)row * 4096 + 2048 + col) = w; } }
	v_mov_b32_e32 v108, v214
	v_mov_b32_e32 v109, v215
	v_mov_b32_e32 v110, v216
	v_mov_b32_e32 v111, v217
	s_mov_b32 s60, 0x13e100
	s_mov_b32 s61, 0
	v_lshl_add_u64 v[214:215], v[254:255], 0, s[60:61]
	global_load_dwordx4 v[214:217], v[214:215], off nt
	v_lshlrev_b32_e32 v146, 16, v111
	v_and_b32_e32 v111, 0xffff0000, v111
	v_lshlrev_b32_e32 v117, 16, v108
	v_and_b32_e32 v108, 0xffff0000, v108
	v_lshlrev_b32_e32 v144, 16, v109
	v_and_b32_e32 v109, 0xffff0000, v109
	v_lshlrev_b32_e32 v145, 16, v110
	v_and_b32_e32 v110, 0xffff0000, v110
	v_mul_f32_e32 v195, 0xbfb8aa3b, v111
	v_mul_f32_e32 v147, 0xbfb8aa3b, v117
	v_mul_f32_e32 v177, 0xbfb8aa3b, v108
	v_mul_f32_e32 v182, 0xbfb8aa3b, v144
	v_mul_f32_e32 v183, 0xbfb8aa3b, v109
	v_mul_f32_e32 v191, 0xbfb8aa3b, v145
	v_mul_f32_e32 v193, 0xbfb8aa3b, v110
	v_mul_f32_e32 v194, 0xbfb8aa3b, v146
	v_exp_f32_e32 v195, v195
	v_exp_f32_e32 v147, v147
	v_exp_f32_e32 v177, v177
	v_exp_f32_e32 v182, v182
	v_exp_f32_e32 v183, v183
	v_exp_f32_e32 v191, v191
	v_exp_f32_e32 v193, v193
	v_exp_f32_e32 v194, v194
	v_add_f32_e32 v195, 1.0, v195
	v_add_f32_e32 v147, 1.0, v147
	v_add_f32_e32 v177, 1.0, v177
	v_add_f32_e32 v182, 1.0, v182
	v_add_f32_e32 v183, 1.0, v183
	v_add_f32_e32 v191, 1.0, v191
	v_add_f32_e32 v193, 1.0, v193
	v_add_f32_e32 v194, 1.0, v194
	v_rcp_f32_e32 v195, v195
	v_rcp_f32_e32 v147, v147
	v_rcp_f32_e32 v177, v177
	v_rcp_f32_e32 v182, v182
	v_rcp_f32_e32 v183, v183
	v_rcp_f32_e32 v191, v191
	v_rcp_f32_e32 v193, v193
	v_rcp_f32_e32 v194, v194
	v_mul_f32_e32 v111, v195, v111
	v_mul_f32_e32 v117, v147, v117
	v_mul_f32_e32 v108, v177, v108
	v_mul_f32_e32 v144, v182, v144
	v_mul_f32_e32 v109, v183, v109
	v_mul_f32_e32 v145, v191, v145
	v_mul_f32_e32 v110, v193, v110
	v_mul_f32_e32 v146, v194, v146
	v_mul_f32_e32 v99, v99, v111
	v_mul_f32_e32 v100, v100, v117
	v_mul_f32_e32 v101, v101, v108
	v_mul_f32_e32 v102, v102, v144
	v_mul_f32_e32 v103, v103, v109
	v_mul_f32_e32 v108, v96, v145
	v_mul_f32_e32 v109, v97, v110
	v_mul_f32_e32 v110, v98, v146
	v_cvt_pk_bf16_f32 v96, v100, v101
	v_cvt_pk_bf16_f32 v97, v102, v103
	v_cvt_pk_bf16_f32 v98, v108, v109
	v_cvt_pk_bf16_f32 v99, v110, v99
	global_store_dwordx4 v[126:127], v[96:99], off
	v_ashrrev_i32_e32 v117, 31, v116
	v_lshlrev_b64 v[98:99], 13, v[116:117]
	v_add_u32_e32 v108, 0x90, v176
	v_lshl_add_u64 v[98:99], s[6:7], 0, v[98:99]
	v_mad_i64_i32 v[96:97], s[2:3], v108, s49, v[178:179]
	v_lshl_add_u64 v[98:99], v[98:99], 0, s[10:11]
	v_lshl_add_u64 v[96:97], v[96:97], 0, s[8:9]
	v_lshl_add_u64 v[116:117], v[98:99], 0, v[174:175]
	v_lshl_add_u64 v[110:111], v[96:97], 0, v[174:175]
	s_waitcnt vmcnt(10)
	v_mov_b32_e32 v100, v218
	v_mov_b32_e32 v101, v219
	v_mov_b32_e32 v102, v220
	v_mov_b32_e32 v103, v221
	s_mov_b32 s60, 0x350100
	s_mov_b32 s61, 0
	v_lshl_add_u64 v[218:219], v[254:255], 0, s[60:61]
	global_load_dwordx4 v[218:221], v[218:219], off nt
	v_lshlrev_b32_e32 v126, 16, v103
	v_and_b32_e32 v103, 0xffff0000, v103
	v_lshlrev_b32_e32 v109, 16, v100
	v_and_b32_e32 v100, 0xffff0000, v100
	v_lshlrev_b32_e32 v118, 16, v101
	v_and_b32_e32 v101, 0xffff0000, v101
	v_lshlrev_b32_e32 v119, 16, v102
	v_and_b32_e32 v102, 0xffff0000, v102
	v_mul_f32_e32 v183, 0xbfb8aa3b, v103
	v_mul_f32_e32 v127, 0xbfb8aa3b, v109
	v_mul_f32_e32 v144, 0xbfb8aa3b, v100
	v_mul_f32_e32 v145, 0xbfb8aa3b, v118
	v_mul_f32_e32 v146, 0xbfb8aa3b, v101
	v_mul_f32_e32 v147, 0xbfb8aa3b, v119
	v_mul_f32_e32 v177, 0xbfb8aa3b, v102
	v_mul_f32_e32 v182, 0xbfb8aa3b, v126
	v_exp_f32_e32 v183, v183
	v_exp_f32_e32 v127, v127
	v_exp_f32_e32 v144, v144
	v_exp_f32_e32 v145, v145
	v_exp_f32_e32 v146, v146
	v_exp_f32_e32 v147, v147
	v_exp_f32_e32 v177, v177
	v_exp_f32_e32 v182, v182
	v_add_f32_e32 v183, 1.0, v183
	v_add_f32_e32 v127, 1.0, v127
	v_add_f32_e32 v144, 1.0, v144
	v_add_f32_e32 v145, 1.0, v145
	v_add_f32_e32 v146, 1.0, v146
	v_add_f32_e32 v147, 1.0, v147
	v_add_f32_e32 v177, 1.0, v177
	v_add_f32_e32 v182, 1.0, v182
	v_rcp_f32_e32 v183, v183
	v_rcp_f32_e32 v127, v127
	v_rcp_f32_e32 v144, v144
	v_rcp_f32_e32 v145, v145
	v_rcp_f32_e32 v146, v146
	v_rcp_f32_e32 v147, v147
	v_rcp_f32_e32 v177, v177
	v_rcp_f32_e32 v182, v182
	v_mul_f32_e32 v103, v183, v103
	v_mul_f32_e32 v109, v127, v109
	v_mul_f32_e32 v100, v144, v100
	v_mul_f32_e32 v118, v145, v118
	v_mul_f32_e32 v101, v146, v101
	v_mul_f32_e32 v119, v147, v119
	v_mul_f32_e32 v102, v177, v102
	v_mul_f32_e32 v126, v182, v126
	v_mul_f32_e32 v91, v91, v103
	v_mul_f32_e32 v92, v92, v109
	v_mul_f32_e32 v93, v93, v100
	v_mul_f32_e32 v94, v94, v118
	v_mul_f32_e32 v95, v95, v101
	v_mul_f32_e32 v100, v88, v119
	v_mul_f32_e32 v101, v89, v102
	v_mul_f32_e32 v102, v90, v126
	v_cvt_pk_bf16_f32 v88, v92, v93
	v_cvt_pk_bf16_f32 v89, v94, v95
	v_cvt_pk_bf16_f32 v90, v100, v101
	v_cvt_pk_bf16_f32 v91, v102, v91
	global_store_dwordx4 v[116:117], v[88:91], off
	v_ashrrev_i32_e32 v109, 31, v108
	v_lshlrev_b64 v[90:91], 13, v[108:109]
	v_add_u32_e32 v100, 0xa0, v176
	v_lshl_add_u64 v[90:91], s[6:7], 0, v[90:91]
	v_mad_i64_i32 v[88:89], s[2:3], v100, s49, v[178:179]
	v_lshl_add_u64 v[90:91], v[90:91], 0, s[10:11]
	v_lshl_add_u64 v[88:89], v[88:89], 0, s[8:9]
	v_lshl_add_u64 v[108:109], v[90:91], 0, v[174:175]
	v_lshl_add_u64 v[102:103], v[88:89], 0, v[174:175]
	s_waitcnt vmcnt(11)
; __device__ __forceinline__ float bflo(unsigned w) { return __uint_as_float(w << 16); }
; __device__ __forceinline__ float bfhi(unsigned w) { return __uint_as_float(w & 0xffff0000u); }
; __device__ __forceinline__ unsigned pk2(float lo, float hi) { unsigned r; asm("v_cvt_pk_bf16_f32 %0, %1, %2" : "=v"(r) : "v"(lo), "v"(hi)); return r; }
; __device__ __forceinline__ float siluf_(float x) { return x * __builtin_amdgcn_rcpf(1.0f + __expf(-x)); }
;     __device__ __forceinline__ void operator()(const f32x4 (&acc)[2][2][4][2], const Unit& u, int wr, int wc, int fr, int fq) const {
;     ...
;             for (int ai = 0; ai < 2; ++ai)
; #pragma unroll
;                 for (int m = 0; m < 4; ++m) { const int row = row0 + ai * HALF + m * 16;
;                     const u32x4 z = __builtin_nontemporal_load((const u32x4*)(proj + (size_t)row * NPROJ + C_ZP + col));
;                     f32x4 v0 = (acc[ai][bj][m][0] + b0) * s0, v1 = (acc[ai][bj][m][1] + b1) * s1;
;                     v0[0] *= siluf_(bflo(z.x)); v0[1] *= siluf_(bfhi(z.x)); v0[2] *= siluf_(bflo(z.y)); v0[3] *= siluf_(bfhi(z.y));
;                     v1[0] *= siluf_(bflo(z.z)); v1[1] *= siluf_(bfhi(z.z)); v1[2] *= siluf_(bflo(z.w)); v1[3] *= siluf_(bfhi(z.w));
;                     u32x4 w; w.x = pk2(v0[0], v0[1]); w.y = pk2(v0[2], v0[3]); w.z = pk2(v1[0], v1[1]); w.w = pk2(v1[2], v1[3]);
;                     *(u32x4*)(a2 + (size_t)row * 4096 + 2048 + col) = w; } }
	v_mov_b32_e32 v92, v222
	v_mov_b32_e32 v93, v223
	v_mov_b32_e32 v94, v224
	v_mov_b32_e32 v95, v225
	s_mov_b32 s60, 0x3ba100
	s_mov_b32 s61, 0
	v_lshl_add_u64 v[222:223], v[254:255], 0, s[60:61]
	global_load_dwordx4 v[222:225], v[222:223], off nt
	v_lshlrev_b32_e32 v116, 16, v95
	v_and_b32_e32 v95, 0xffff0000, v95
	v_lshlrev_b32_e32 v101, 16, v92
	v_and_b32_e32 v92, 0xffff0000, v92
	v_lshlrev_b32_e32 v110, 16, v93
	v_and_b32_e32 v93, 0xffff0000, v93
	v_lshlrev_b32_e32 v111, 16, v94
	v_and_b32_e32 v94, 0xffff0000, v94
	v_mul_f32_e32 v146, 0xbfb8aa3b, v95
	v_mul_f32_e32 v117, 0xbfb8aa3b, v101
	v_mul_f32_e32 v118, 0xbfb8aa3b, v92
	v_mul_f32_e32 v119, 0xbfb8aa3b, v110
	v_mul_f32_e32 v126, 0xbfb8aa3b, v93
	v_mul_f32_e32 v127, 0xbfb8aa3b, v111
	v_mul_f32_e32 v144, 0xbfb8aa3b, v94
	v_mul_f32_e32 v145, 0xbfb8aa3b, v116
	v_exp_f32_e32 v146, v146
	v_exp_f32_e32 v117, v117
	v_exp_f32_e32 v118, v118
	v_exp_f32_e32 v119, v119
	v_exp_f32_e32 v126, v126
	v_exp_f32_e32 v127, v127
	v_exp_f32_e32 v144, v144
	v_exp_f32_e32 v145, v145
	v_add_f32_e32 v146, 1.0, v146
	v_add_f32_e32 v117, 1.0, v117
	v_add_f32_e32 v118, 1.0, v118
	v_add_f32_e32 v119, 1.0, v119
	v_add_f32_e32 v126, 1.0, v126
	v_add_f32_e32 v127, 1.0, v127
	v_add_f32_e32 v144, 1.0, v144
	v_add_f32_e32 v145, 1.0, v145
	v_rcp_f32_e32 v146, v146
	v_rcp_f32_e32 v117, v117
	v_rcp_f32_e32 v118, v118
	v_rcp_f32_e32 v119, v119
	v_rcp_f32_e32 v126, v126
	v_rcp_f32_e32 v127, v127
	v_rcp_f32_e32 v144, v144
	v_rcp_f32_e32 v145, v145
	v_mul_f32_e32 v95, v146, v95
	v_mul_f32_e32 v101, v117, v101
	v_mul_f32_e32 v92, v118, v92
	v_mul_f32_e32 v110, v119, v110
	v_mul_f32_e32 v93, v126, v93
	v_mul_f32_e32 v111, v127, v111
	v_mul_f32_e32 v94, v144, v94
	v_mul_f32_e32 v116, v145, v116
	v_mul_f32_e32 v83, v83, v95
	v_mul_f32_e32 v84, v84, v101
	v_mul_f32_e32 v85, v85, v92
	v_mul_f32_e32 v86, v86, v110
	v_mul_f32_e32 v87, v87, v93
	v_mul_f32_e32 v92, v80, v111
	v_mul_f32_e32 v93, v81, v94
	v_mul_f32_e32 v94, v82, v116
	v_cvt_pk_bf16_f32 v80, v84, v85
	v_cvt_pk_bf16_f32 v81, v86, v87
	v_cvt_pk_bf16_f32 v82, v92, v93
	v_cvt_pk_bf16_f32 v83, v94, v83
	global_store_dwordx4 v[108:109], v[80:83], off
	v_ashrrev_i32_e32 v101, 31, v100
	v_lshlrev_b64 v[84:85], 13, v[100:101]
	v_add_u32_e32 v80, 0xb0, v176
	v_lshl_add_u64 v[84:85], s[6:7], 0, v[84:85]
	v_mad_i64_i32 v[82:83], s[2:3], v80, s49, v[178:179]
	v_lshl_add_u64 v[84:85], v[84:85], 0, s[10:11]
	v_lshl_add_u64 v[82:83], v[82:83], 0, s[8:9]
	v_lshl_add_u64 v[100:101], v[84:85], 0, v[174:175]
	v_lshl_add_u64 v[86:87], v[82:83], 0, v[174:175]
	s_waitcnt vmcnt(12)
	v_mov_b32_e32 v92, v226
	v_mov_b32_e32 v93, v227
	v_mov_b32_e32 v94, v228
	v_mov_b32_e32 v95, v229
	s_mov_b32 s60, 0x424100
	s_mov_b32 s61, 0
	v_lshl_add_u64 v[226:227], v[254:255], 0, s[60:61]
	global_load_dwordx4 v[226:229], v[226:227], off nt
	v_lshlrev_b32_e32 v108, 16, v95
	v_and_b32_e32 v95, 0xffff0000, v95
	v_lshlrev_b32_e32 v81, 16, v92
	v_and_b32_e32 v92, 0xffff0000, v92
	v_lshlrev_b32_e32 v102, 16, v93
	v_and_b32_e32 v93, 0xffff0000, v93
	v_lshlrev_b32_e32 v103, 16, v94
	v_and_b32_e32 v94, 0xffff0000, v94
	v_mul_f32_e32 v126, 0xbfb8aa3b, v95
	v_mul_f32_e32 v109, 0xbfb8aa3b, v81
	v_mul_f32_e32 v110, 0xbfb8aa3b, v92
	v_mul_f32_e32 v111, 0xbfb8aa3b, v102
	v_mul_f32_e32 v116, 0xbfb8aa3b, v93
	v_mul_f32_e32 v117, 0xbfb8aa3b, v103
	v_mul_f32_e32 v118, 0xbfb8aa3b, v94
	v_mul_f32_e32 v119, 0xbfb8aa3b, v108
	v_exp_f32_e32 v126, v126
	v_exp_f32_e32 v109, v109
	v_exp_f32_e32 v110, v110
	v_exp_f32_e32 v111, v111
	v_exp_f32_e32 v116, v116
	v_exp_f32_e32 v117, v117
	v_exp_f32_e32 v118, v118
	v_exp_f32_e32 v119, v119
	v_add_f32_e32 v126, 1.0, v126
	v_add_f32_e32 v109, 1.0, v109
	v_add_f32_e32 v110, 1.0, v110
	v_add_f32_e32 v111, 1.0, v111
	v_add_f32_e32 v116, 1.0, v116
	v_add_f32_e32 v117, 1.0, v117
	v_add_f32_e32 v118, 1.0, v118
	v_add_f32_e32 v119, 1.0, v119
	v_rcp_f32_e32 v126, v126
	v_rcp_f32_e32 v109, v109
	v_rcp_f32_e32 v110, v110
	v_rcp_f32_e32 v111, v111
	v_rcp_f32_e32 v116, v116
	v_rcp_f32_e32 v117, v117
	v_rcp_f32_e32 v118, v118
	v_rcp_f32_e32 v119, v119
	v_mul_f32_e32 v95, v126, v95
	v_mul_f32_e32 v81, v109, v81
	v_mul_f32_e32 v92, v110, v92
	v_mul_f32_e32 v102, v111, v102
	v_mul_f32_e32 v93, v116, v93
	v_mul_f32_e32 v103, v117, v103
	v_mul_f32_e32 v94, v118, v94
	v_mul_f32_e32 v108, v119, v108
	v_mul_f32_e32 v75, v75, v95
	v_mul_f32_e32 v76, v76, v81
	v_mul_f32_e32 v77, v77, v92
	v_mul_f32_e32 v78, v78, v102
	v_mul_f32_e32 v79, v79, v93
	v_mul_f32_e32 v81, v72, v103
	v_mul_f32_e32 v92, v73, v94
	v_mul_f32_e32 v93, v74, v108
	v_cvt_pk_bf16_f32 v72, v76, v77
	v_cvt_pk_bf16_f32 v73, v78, v79
	v_cvt_pk_bf16_f32 v74, v81, v92
	v_cvt_pk_bf16_f32 v75, v93, v75
	global_store_dwordx4 v[100:101], v[72:75], off
	v_ashrrev_i32_e32 v81, 31, v80
	v_lshlrev_b64 v[76:77], 13, v[80:81]
	v_lshl_add_u64 v[76:77], s[6:7], 0, v[76:77]
	v_lshl_add_u64 v[80:81], v[76:77], 0, s[10:11]
	v_lshl_add_u64 v[76:77], v[80:81], 0, v[174:175]
	v_and_b32_e32 v109, 0xffff0000, v151
	v_lshlrev_b32_e32 v108, 16, v151
	s_waitcnt vmcnt(13)
; __device__ __forceinline__ float bflo(unsigned w) { return __uint_as_float(w << 16); }
; __device__ __forceinline__ float bfhi(unsigned w) { return __uint_as_float(w & 0xffff0000u); }
; __device__ __forceinline__ unsigned pk2(float lo, float hi) { unsigned r; asm("v_cvt_pk_bf16_f32 %0, %1, %2" : "=v"(r) : "v"(lo), "v"(hi)); return r; }
; __device__ __forceinline__ float siluf_(float x) { return x * __builtin_amdgcn_rcpf(1.0f + __expf(-x)); }
;     __device__ __forceinline__ void operator()(const f32x4 (&acc)[2][2][4][2], const Unit& u, int wr, int wc, int fr, int fq) const {
;     ...
;         for (int bj = 0; bj < 2; ++bj) { const int col = col0 + bj * HALF;
;             const f32x4 b0 = *(const f32x4*)(bias + col), b1 = *(const f32x4*)(bias + col + 4), s0 = *(const f32x4*)(scale + col), s1 = *(const f32x4*)(scale + col + 4);
; #pragma unroll
;             for (int ai = 0; ai < 2; ++ai)
; #pragma unroll
;                 for (int m = 0; m < 4; ++m) { const int row = row0 + ai * HALF + m * 16;
;                     const u32x4 z = __builtin_nontemporal_load((const u32x4*)(proj + (size_t)row * NPROJ + C_ZP + col));
;                     f32x4 v0 = (acc[ai][bj][m][0] + b0) * s0, v1 = (acc[ai][bj][m][1] + b1) * s1;
;                     v0[0] *= siluf_(bflo(z.x)); v0[1] *= siluf_(bfhi(z.x)); v0[2] *= siluf_(bflo(z.y)); v0[3] *= siluf_(bfhi(z.y));
;                     v1[0] *= siluf_(bflo(z.z)); v1[1] *= siluf_(bfhi(z.z)); v1[2] *= siluf_(bflo(z.w)); v1[3] *= siluf_(bfhi(z.w));
;                     u32x4 w; w.x = pk2(v0[0], v0[1]); w.y = pk2(v0[2], v0[3]); w.z = pk2(v1[0], v1[1]); w.w = pk2(v1[2], v1[3]);
;                     *(u32x4*)(a2 + (size_t)row * 4096 + 2048 + col) = w; } }
	v_mov_b32_e32 v72, v230
	v_mov_b32_e32 v73, v231
	v_mov_b32_e32 v74, v232
	v_mov_b32_e32 v75, v233
	s_mov_b32 s60, 0x48e100
	s_mov_b32 s61, 0
	v_lshl_add_u64 v[230:231], v[254:255], 0, s[60:61]
	global_load_dwordx4 v[230:233], v[230:231], off nt
	v_lshlrev_b32_e32 v87, 16, v75
	v_and_b32_e32 v75, 0xffff0000, v75
	v_lshlrev_b32_e32 v78, 16, v72
	v_and_b32_e32 v72, 0xffff0000, v72
	v_lshlrev_b32_e32 v79, 16, v73
	v_and_b32_e32 v73, 0xffff0000, v73
	v_lshlrev_b32_e32 v86, 16, v74
	v_and_b32_e32 v74, 0xffff0000, v74
	v_mul_f32_e32 v103, 0xbfb8aa3b, v75
	v_mul_f32_e32 v92, 0xbfb8aa3b, v78
	v_mul_f32_e32 v93, 0xbfb8aa3b, v72
	v_mul_f32_e32 v94, 0xbfb8aa3b, v79
	v_mul_f32_e32 v95, 0xbfb8aa3b, v73
	v_mul_f32_e32 v100, 0xbfb8aa3b, v86
	v_mul_f32_e32 v101, 0xbfb8aa3b, v74
	v_mul_f32_e32 v102, 0xbfb8aa3b, v87
	v_exp_f32_e32 v103, v103
	v_exp_f32_e32 v92, v92
	v_exp_f32_e32 v93, v93
	v_exp_f32_e32 v94, v94
	v_exp_f32_e32 v95, v95
	v_exp_f32_e32 v100, v100
	v_exp_f32_e32 v101, v101
	v_exp_f32_e32 v102, v102
	v_add_f32_e32 v103, 1.0, v103
	v_add_f32_e32 v92, 1.0, v92
	v_add_f32_e32 v93, 1.0, v93
	v_add_f32_e32 v94, 1.0, v94
	v_add_f32_e32 v95, 1.0, v95
	v_add_f32_e32 v100, 1.0, v100
	v_add_f32_e32 v101, 1.0, v101
	v_add_f32_e32 v102, 1.0, v102
	v_rcp_f32_e32 v103, v103
	v_rcp_f32_e32 v92, v92
	v_rcp_f32_e32 v93, v93
	v_rcp_f32_e32 v94, v94
	v_rcp_f32_e32 v95, v95
	v_rcp_f32_e32 v100, v100
	v_rcp_f32_e32 v101, v101
	v_rcp_f32_e32 v102, v102
	v_mul_f32_e32 v75, v103, v75
	v_mul_f32_e32 v78, v92, v78
	v_mul_f32_e32 v72, v93, v72
	v_mul_f32_e32 v79, v94, v79
	v_mul_f32_e32 v73, v95, v73
	v_mul_f32_e32 v86, v100, v86
	v_mul_f32_e32 v74, v101, v74
	v_mul_f32_e32 v87, v102, v87
	v_mul_f32_e32 v67, v67, v75
	v_mul_f32_e32 v68, v68, v78
	v_mul_f32_e32 v69, v69, v72
	v_mul_f32_e32 v70, v70, v79
	v_mul_f32_e32 v71, v71, v73
	v_mul_f32_e32 v72, v64, v86
	v_mul_f32_e32 v73, v65, v74
	v_mul_f32_e32 v74, v66, v87
	v_cvt_pk_bf16_f32 v64, v68, v69
	v_cvt_pk_bf16_f32 v65, v70, v71
	v_cvt_pk_bf16_f32 v66, v72, v73
	v_cvt_pk_bf16_f32 v67, v74, v67
	global_store_dwordx4 v[76:77], v[64:67], off
	v_mov_b32_e32 v76, v234
	v_mov_b32_e32 v77, v235
	v_mov_b32_e32 v78, v236
	v_mov_b32_e32 v79, v237
	s_nop 0
	v_mov_b32_e32 v72, v238
	v_mov_b32_e32 v73, v239
	v_mov_b32_e32 v74, v240
	v_mov_b32_e32 v75, v241
	v_mov_b32_e32 v68, v246
	v_mov_b32_e32 v69, v247
	v_mov_b32_e32 v70, v248
	v_mov_b32_e32 v71, v249
	v_mov_b32_e32 v64, v250
	v_mov_b32_e32 v65, v251
	v_mov_b32_e32 v66, v252
	v_mov_b32_e32 v67, v253
	v_lshl_add_u64 v[86:87], v[124:125], 0, v[168:169]
	v_lshlrev_b32_e32 v94, 16, v148
	v_and_b32_e32 v95, 0xffff0000, v148
	v_lshlrev_b32_e32 v100, 16, v149
	v_and_b32_e32 v101, 0xffff0000, v149
	v_lshlrev_b32_e32 v102, 16, v150
	v_and_b32_e32 v103, 0xffff0000, v150
	v_mul_f32_e32 v125, 0xbfb8aa3b, v109
	v_mul_f32_e32 v110, 0xbfb8aa3b, v94
	v_mul_f32_e32 v111, 0xbfb8aa3b, v95
	v_mul_f32_e32 v116, 0xbfb8aa3b, v100
	v_mul_f32_e32 v117, 0xbfb8aa3b, v101
	v_mul_f32_e32 v118, 0xbfb8aa3b, v102
	v_mul_f32_e32 v119, 0xbfb8aa3b, v103
	v_mul_f32_e32 v124, 0xbfb8aa3b, v108
	v_exp_f32_e32 v125, v125
	v_exp_f32_e32 v110, v110
	v_exp_f32_e32 v111, v111
	v_exp_f32_e32 v116, v116
	v_exp_f32_e32 v117, v117
	v_exp_f32_e32 v118, v118
	v_exp_f32_e32 v119, v119
	v_exp_f32_e32 v124, v124
	v_add_f32_e32 v125, 1.0, v125
	v_add_f32_e32 v110, 1.0, v110
	v_add_f32_e32 v111, 1.0, v111
	v_add_f32_e32 v116, 1.0, v116
	v_add_f32_e32 v117, 1.0, v117
	v_add_f32_e32 v118, 1.0, v118
	v_add_f32_e32 v119, 1.0, v119
	v_add_f32_e32 v124, 1.0, v124
	v_rcp_f32_e32 v125, v125
	v_rcp_f32_e32 v110, v110
	v_rcp_f32_e32 v111, v111
	v_rcp_f32_e32 v116, v116
	v_rcp_f32_e32 v117, v117
	v_rcp_f32_e32 v118, v118
	v_rcp_f32_e32 v119, v119
	v_rcp_f32_e32 v124, v124
	v_mul_f32_e32 v109, v125, v109
	v_lshl_add_u64 v[92:93], v[180:181], 0, v[168:169]
	v_mul_f32_e32 v94, v110, v94
	v_mul_f32_e32 v95, v111, v95
	v_mul_f32_e32 v100, v116, v100
	v_mul_f32_e32 v101, v117, v101
	v_mul_f32_e32 v102, v118, v102
	v_mul_f32_e32 v103, v119, v103
	v_mul_f32_e32 v108, v124, v108
	s_nop 0
	v_pk_add_f32 v[62:63], v[62:63], v[78:79]
	v_pk_add_f32 v[58:59], v[58:59], v[74:75]
	v_pk_add_f32 v[60:61], v[60:61], v[76:77]
	v_pk_add_f32 v[56:57], v[56:57], v[72:73]
	v_pk_mul_f32 v[58:59], v[58:59], v[66:67]
	v_pk_mul_f32 v[62:63], v[62:63], v[70:71]
	v_pk_mul_f32 v[60:61], v[60:61], v[68:69]
	v_pk_mul_f32 v[56:57], v[56:57], v[64:65]
	v_mul_f32_e32 v59, v59, v109
	v_mul_f32_e32 v60, v60, v94
	v_mul_f32_e32 v61, v61, v95
	v_mul_f32_e32 v62, v62, v100
	v_mul_f32_e32 v63, v63, v101
	v_mul_f32_e32 v94, v56, v102
	v_mul_f32_e32 v95, v57, v103
	v_mul_f32_e32 v100, v58, v108
	v_cvt_pk_bf16_f32 v56, v60, v61
	v_cvt_pk_bf16_f32 v57, v62, v63
	v_cvt_pk_bf16_f32 v58, v94, v95
	v_cvt_pk_bf16_f32 v59, v100, v59
	global_store_dwordx4 v[92:93], v[56:59], off
	v_pk_add_f32 v[50:51], v[50:51], v[74:75]
	v_pk_add_f32 v[54:55], v[54:55], v[78:79]
	v_pk_add_f32 v[52:53], v[52:53], v[76:77]
	v_pk_add_f32 v[48:49], v[48:49], v[72:73]
	v_pk_mul_f32 v[50:51], v[50:51], v[66:67]
	v_lshl_add_u64 v[62:63], v[122:123], 0, v[168:169]
	v_pk_mul_f32 v[54:55], v[54:55], v[70:71]
	v_pk_mul_f32 v[52:53], v[52:53], v[68:69]
	v_pk_mul_f32 v[48:49], v[48:49], v[64:65]
	v_lshl_add_u64 v[60:61], v[120:121], 0, v[168:169]
	v_pk_add_f32 v[42:43], v[42:43], v[74:75]
	v_pk_add_f32 v[46:47], v[46:47], v[78:79]
	v_pk_add_f32 v[44:45], v[44:45], v[76:77]
	v_pk_add_f32 v[40:41], v[40:41], v[72:73]
	v_pk_mul_f32 v[42:43], v[42:43], v[66:67]
	v_pk_mul_f32 v[46:47], v[46:47], v[70:71]
	v_pk_mul_f32 v[44:45], v[44:45], v[68:69]
	v_pk_mul_f32 v[40:41], v[40:41], v[64:65]
	v_pk_add_f32 v[34:35], v[34:35], v[74:75]
; __device__ __forceinline__ float bflo(unsigned w) { return __uint_as_float(w << 16); }
; __device__ __forceinline__ float bfhi(unsigned w) { return __uint_as_float(w & 0xffff0000u); }
; __device__ __forceinline__ unsigned pk2(float lo, float hi) { unsigned r; asm("v_cvt_pk_bf16_f32 %0, %1, %2" : "=v"(r) : "v"(lo), "v"(hi)); return r; }
; __device__ __forceinline__ float siluf_(float x) { return x * __builtin_amdgcn_rcpf(1.0f + __expf(-x)); }
;     __device__ __forceinline__ void operator()(const f32x4 (&acc)[2][2][4][2], const Unit& u, int wr, int wc, int fr, int fq) const {
;     ...
;             for (int ai = 0; ai < 2; ++ai)
; #pragma unroll
;                 for (int m = 0; m < 4; ++m) { const int row = row0 + ai * HALF + m * 16;
;                     const u32x4 z = __builtin_nontemporal_load((const u32x4*)(proj + (size_t)row * NPROJ + C_ZP + col));
;                     f32x4 v0 = (acc[ai][bj][m][0] + b0) * s0, v1 = (acc[ai][bj][m][1] + b1) * s1;
;                     v0[0] *= siluf_(bflo(z.x)); v0[1] *= siluf_(bfhi(z.x)); v0[2] *= siluf_(bflo(z.y)); v0[3] *= siluf_(bfhi(z.y));
;                     v1[0] *= siluf_(bflo(z.z)); v1[1] *= siluf_(bfhi(z.z)); v1[2] *= siluf_(bflo(z.w)); v1[3] *= siluf_(bfhi(z.w));
;                     u32x4 w; w.x = pk2(v0[0], v0[1]); w.y = pk2(v0[2], v0[3]); w.z = pk2(v1[0], v1[1]); w.w = pk2(v1[2], v1[3]);
;                     *(u32x4*)(a2 + (size_t)row * 4096 + 2048 + col) = w; } }
	v_pk_add_f32 v[38:39], v[38:39], v[78:79]
	v_pk_add_f32 v[36:37], v[36:37], v[76:77]
	v_pk_add_f32 v[32:33], v[32:33], v[72:73]
	v_pk_mul_f32 v[34:35], v[34:35], v[66:67]
	v_pk_mul_f32 v[38:39], v[38:39], v[70:71]
	v_pk_mul_f32 v[36:37], v[36:37], v[68:69]
	v_pk_mul_f32 v[32:33], v[32:33], v[64:65]
	v_pk_add_f32 v[26:27], v[26:27], v[74:75]
	v_pk_add_f32 v[30:31], v[30:31], v[78:79]
	v_pk_add_f32 v[28:29], v[28:29], v[76:77]
	v_pk_add_f32 v[24:25], v[24:25], v[72:73]
	v_pk_mul_f32 v[26:27], v[26:27], v[66:67]
	v_pk_mul_f32 v[30:31], v[30:31], v[70:71]
	v_pk_mul_f32 v[28:29], v[28:29], v[68:69]
	v_pk_mul_f32 v[24:25], v[24:25], v[64:65]
	v_pk_add_f32 v[18:19], v[18:19], v[74:75]
	v_pk_add_f32 v[22:23], v[22:23], v[78:79]
	v_pk_add_f32 v[20:21], v[20:21], v[76:77]
	v_pk_add_f32 v[16:17], v[16:17], v[72:73]
	v_pk_mul_f32 v[18:19], v[18:19], v[66:67]
	v_pk_mul_f32 v[22:23], v[22:23], v[70:71]
	v_pk_mul_f32 v[20:21], v[20:21], v[68:69]
	v_pk_mul_f32 v[16:17], v[16:17], v[64:65]
	v_pk_add_f32 v[10:11], v[10:11], v[74:75]
	v_pk_add_f32 v[14:15], v[14:15], v[78:79]
	v_pk_add_f32 v[12:13], v[12:13], v[76:77]
	v_pk_add_f32 v[8:9], v[8:9], v[72:73]
	v_pk_mul_f32 v[10:11], v[10:11], v[66:67]
	v_pk_mul_f32 v[14:15], v[14:15], v[70:71]
	v_pk_mul_f32 v[12:13], v[12:13], v[68:69]
	v_pk_mul_f32 v[8:9], v[8:9], v[64:65]
	v_pk_add_f32 v[2:3], v[2:3], v[74:75]
	v_pk_add_f32 v[6:7], v[6:7], v[78:79]
	v_pk_add_f32 v[4:5], v[4:5], v[76:77]
	v_pk_add_f32 v[0:1], v[0:1], v[72:73]
	v_pk_mul_f32 v[2:3], v[2:3], v[66:67]
	v_pk_mul_f32 v[6:7], v[6:7], v[70:71]
	v_pk_mul_f32 v[4:5], v[4:5], v[68:69]
	v_pk_mul_f32 v[0:1], v[0:1], v[64:65]
	s_waitcnt vmcnt(14)
	v_mov_b32_e32 v56, v206
	v_mov_b32_e32 v57, v207
	v_mov_b32_e32 v58, v208
	v_mov_b32_e32 v59, v209
	v_lshlrev_b32_e32 v93, 16, v59
	v_and_b32_e32 v59, 0xffff0000, v59
	v_lshlrev_b32_e32 v86, 16, v56
	v_and_b32_e32 v56, 0xffff0000, v56
	v_lshlrev_b32_e32 v87, 16, v57
	v_and_b32_e32 v57, 0xffff0000, v57
	v_lshlrev_b32_e32 v92, 16, v58
	v_and_b32_e32 v58, 0xffff0000, v58
	v_mul_f32_e32 v109, 0xbfb8aa3b, v59
	v_mul_f32_e32 v94, 0xbfb8aa3b, v86
	v_mul_f32_e32 v95, 0xbfb8aa3b, v56
	v_mul_f32_e32 v100, 0xbfb8aa3b, v87
	v_mul_f32_e32 v101, 0xbfb8aa3b, v57
	v_mul_f32_e32 v102, 0xbfb8aa3b, v92
	v_mul_f32_e32 v103, 0xbfb8aa3b, v58
	v_mul_f32_e32 v108, 0xbfb8aa3b, v93
	v_exp_f32_e32 v109, v109
	v_exp_f32_e32 v94, v94
	v_exp_f32_e32 v95, v95
	v_exp_f32_e32 v100, v100
	v_exp_f32_e32 v101, v101
	v_exp_f32_e32 v102, v102
	v_exp_f32_e32 v103, v103
	v_exp_f32_e32 v108, v108
	v_add_f32_e32 v109, 1.0, v109
	v_add_f32_e32 v94, 1.0, v94
	v_add_f32_e32 v95, 1.0, v95
	v_add_f32_e32 v100, 1.0, v100
	v_add_f32_e32 v101, 1.0, v101
	v_add_f32_e32 v102, 1.0, v102
	v_add_f32_e32 v103, 1.0, v103
	v_add_f32_e32 v108, 1.0, v108
	v_rcp_f32_e32 v109, v109
	v_rcp_f32_e32 v94, v94
	v_rcp_f32_e32 v95, v95
	v_rcp_f32_e32 v100, v100
	v_rcp_f32_e32 v101, v101
	v_rcp_f32_e32 v102, v102
	v_rcp_f32_e32 v103, v103
	v_rcp_f32_e32 v108, v108
	v_mul_f32_e32 v59, v109, v59
	v_mul_f32_e32 v86, v94, v86
	v_mul_f32_e32 v56, v95, v56
	v_mul_f32_e32 v87, v100, v87
	v_mul_f32_e32 v57, v101, v57
	v_mul_f32_e32 v92, v102, v92
	v_mul_f32_e32 v58, v103, v58
	v_mul_f32_e32 v93, v108, v93
	v_mul_f32_e32 v51, v51, v59
	v_mul_f32_e32 v52, v52, v86
	v_mul_f32_e32 v53, v53, v56
	v_mul_f32_e32 v54, v54, v87
	v_mul_f32_e32 v55, v55, v57
	v_mul_f32_e32 v56, v48, v92
	v_mul_f32_e32 v57, v49, v58
	v_mul_f32_e32 v58, v50, v93
	v_cvt_pk_bf16_f32 v48, v52, v53
	v_cvt_pk_bf16_f32 v49, v54, v55
	v_cvt_pk_bf16_f32 v50, v56, v57
	v_cvt_pk_bf16_f32 v51, v58, v51
	global_store_dwordx4 v[62:63], v[48:51], off
	v_lshl_add_u64 v[54:55], v[114:115], 0, v[168:169]
	v_lshl_add_u64 v[52:53], v[112:113], 0, v[168:169]
	s_waitcnt vmcnt(13)
	v_mov_b32_e32 v48, v210
	v_mov_b32_e32 v49, v211
	v_mov_b32_e32 v50, v212
	v_mov_b32_e32 v51, v213
	v_lshlrev_b32_e32 v59, 16, v51
	v_and_b32_e32 v51, 0xffff0000, v51
	v_lshlrev_b32_e32 v56, 16, v48
	v_and_b32_e32 v48, 0xffff0000, v48
	v_lshlrev_b32_e32 v57, 16, v49
	v_and_b32_e32 v49, 0xffff0000, v49
	v_lshlrev_b32_e32 v58, 16, v50
	v_and_b32_e32 v50, 0xffff0000, v50
	v_mul_f32_e32 v93, 0xbfb8aa3b, v51
	v_mul_f32_e32 v60, 0xbfb8aa3b, v56
	v_mul_f32_e32 v61, 0xbfb8aa3b, v48
	v_mul_f32_e32 v62, 0xbfb8aa3b, v57
	v_mul_f32_e32 v63, 0xbfb8aa3b, v49
	v_mul_f32_e32 v86, 0xbfb8aa3b, v58
	v_mul_f32_e32 v87, 0xbfb8aa3b, v50
	v_mul_f32_e32 v92, 0xbfb8aa3b, v59
	v_exp_f32_e32 v93, v93
	v_exp_f32_e32 v60, v60
	v_exp_f32_e32 v61, v61
	v_exp_f32_e32 v62, v62
	v_exp_f32_e32 v63, v63
	v_exp_f32_e32 v86, v86
	v_exp_f32_e32 v87, v87
	v_exp_f32_e32 v92, v92
	v_add_f32_e32 v93, 1.0, v93
	v_add_f32_e32 v60, 1.0, v60
	v_add_f32_e32 v61, 1.0, v61
	v_add_f32_e32 v62, 1.0, v62
	v_add_f32_e32 v63, 1.0, v63
	v_add_f32_e32 v86, 1.0, v86
	v_add_f32_e32 v87, 1.0, v87
	v_add_f32_e32 v92, 1.0, v92
	v_rcp_f32_e32 v93, v93
	v_rcp_f32_e32 v60, v60
	v_rcp_f32_e32 v61, v61
	v_rcp_f32_e32 v62, v62
	v_rcp_f32_e32 v63, v63
	v_rcp_f32_e32 v86, v86
	v_rcp_f32_e32 v87, v87
	v_rcp_f32_e32 v92, v92
	v_mul_f32_e32 v51, v93, v51
	v_mul_f32_e32 v56, v60, v56
	v_mul_f32_e32 v48, v61, v48
	v_mul_f32_e32 v57, v62, v57
	v_mul_f32_e32 v49, v63, v49
	v_mul_f32_e32 v58, v86, v58
	v_mul_f32_e32 v50, v87, v50
	v_mul_f32_e32 v59, v92, v59
	v_mul_f32_e32 v43, v43, v51
	v_mul_f32_e32 v44, v44, v56
	v_mul_f32_e32 v45, v45, v48
	v_mul_f32_e32 v46, v46, v57
	v_mul_f32_e32 v47, v47, v49
	v_mul_f32_e32 v48, v40, v58
	v_mul_f32_e32 v49, v41, v50
	v_mul_f32_e32 v50, v42, v59
	v_cvt_pk_bf16_f32 v40, v44, v45
	v_cvt_pk_bf16_f32 v41, v46, v47
	v_cvt_pk_bf16_f32 v42, v48, v49
	v_cvt_pk_bf16_f32 v43, v50, v43
	global_store_dwordx4 v[54:55], v[40:43], off
	v_lshl_add_u64 v[46:47], v[106:107], 0, v[168:169]
	v_lshl_add_u64 v[44:45], v[104:105], 0, v[168:169]
	s_waitcnt vmcnt(12)
; __device__ __forceinline__ float bflo(unsigned w) { return __uint_as_float(w << 16); }
; __device__ __forceinline__ float bfhi(unsigned w) { return __uint_as_float(w & 0xffff0000u); }
; __device__ __forceinline__ unsigned pk2(float lo, float hi) { unsigned r; asm("v_cvt_pk_bf16_f32 %0, %1, %2" : "=v"(r) : "v"(lo), "v"(hi)); return r; }
; __device__ __forceinline__ float siluf_(float x) { return x * __builtin_amdgcn_rcpf(1.0f + __expf(-x)); }
;     __device__ __forceinline__ void operator()(const f32x4 (&acc)[2][2][4][2], const Unit& u, int wr, int wc, int fr, int fq) const {
;     ...
;             for (int ai = 0; ai < 2; ++ai)
; #pragma unroll
;                 for (int m = 0; m < 4; ++m) { const int row = row0 + ai * HALF + m * 16;
;                     const u32x4 z = __builtin_nontemporal_load((const u32x4*)(proj + (size_t)row * NPROJ + C_ZP + col));
;                     f32x4 v0 = (acc[ai][bj][m][0] + b0) * s0, v1 = (acc[ai][bj][m][1] + b1) * s1;
;                     v0[0] *= siluf_(bflo(z.x)); v0[1] *= siluf_(bfhi(z.x)); v0[2] *= siluf_(bflo(z.y)); v0[3] *= siluf_(bfhi(z.y));
;                     v1[0] *= siluf_(bflo(z.z)); v1[1] *= siluf_(bfhi(z.z)); v1[2] *= siluf_(bflo(z.w)); v1[3] *= siluf_(bfhi(z.w));
;                     u32x4 w; w.x = pk2(v0[0], v0[1]); w.y = pk2(v0[2], v0[3]); w.z = pk2(v1[0], v1[1]); w.w = pk2(v1[2], v1[3]);
;                     *(u32x4*)(a2 + (size_t)row * 4096 + 2048 + col) = w; } }
	v_mov_b32_e32 v40, v214
	v_mov_b32_e32 v41, v215
	v_mov_b32_e32 v42, v216
	v_mov_b32_e32 v43, v217
	v_lshlrev_b32_e32 v51, 16, v43
	v_and_b32_e32 v43, 0xffff0000, v43
	v_lshlrev_b32_e32 v48, 16, v40
	v_and_b32_e32 v40, 0xffff0000, v40
	v_lshlrev_b32_e32 v49, 16, v41
	v_and_b32_e32 v41, 0xffff0000, v41
	v_lshlrev_b32_e32 v50, 16, v42
	v_and_b32_e32 v42, 0xffff0000, v42
	v_mul_f32_e32 v59, 0xbfb8aa3b, v43
	v_mul_f32_e32 v52, 0xbfb8aa3b, v48
	v_mul_f32_e32 v53, 0xbfb8aa3b, v40
	v_mul_f32_e32 v54, 0xbfb8aa3b, v49
	v_mul_f32_e32 v55, 0xbfb8aa3b, v41
	v_mul_f32_e32 v56, 0xbfb8aa3b, v50
	v_mul_f32_e32 v57, 0xbfb8aa3b, v42
	v_mul_f32_e32 v58, 0xbfb8aa3b, v51
	v_exp_f32_e32 v59, v59
	v_exp_f32_e32 v52, v52
	v_exp_f32_e32 v53, v53
	v_exp_f32_e32 v54, v54
	v_exp_f32_e32 v55, v55
	v_exp_f32_e32 v56, v56
	v_exp_f32_e32 v57, v57
	v_exp_f32_e32 v58, v58
	v_add_f32_e32 v59, 1.0, v59
	v_add_f32_e32 v52, 1.0, v52
	v_add_f32_e32 v53, 1.0, v53
	v_add_f32_e32 v54, 1.0, v54
	v_add_f32_e32 v55, 1.0, v55
	v_add_f32_e32 v56, 1.0, v56
	v_add_f32_e32 v57, 1.0, v57
	v_add_f32_e32 v58, 1.0, v58
	v_rcp_f32_e32 v59, v59
	v_rcp_f32_e32 v52, v52
	v_rcp_f32_e32 v53, v53
	v_rcp_f32_e32 v54, v54
	v_rcp_f32_e32 v55, v55
	v_rcp_f32_e32 v56, v56
	v_rcp_f32_e32 v57, v57
	v_rcp_f32_e32 v58, v58
	v_mul_f32_e32 v43, v59, v43
	v_mul_f32_e32 v48, v52, v48
	v_mul_f32_e32 v40, v53, v40
	v_mul_f32_e32 v49, v54, v49
	v_mul_f32_e32 v41, v55, v41
	v_mul_f32_e32 v50, v56, v50
	v_mul_f32_e32 v42, v57, v42
	v_mul_f32_e32 v51, v58, v51
	v_mul_f32_e32 v35, v35, v43
	v_mul_f32_e32 v36, v36, v48
	v_mul_f32_e32 v37, v37, v40
	v_mul_f32_e32 v38, v38, v49
	v_mul_f32_e32 v39, v39, v41
	v_mul_f32_e32 v40, v32, v50
	v_mul_f32_e32 v41, v33, v42
	v_mul_f32_e32 v42, v34, v51
	v_cvt_pk_bf16_f32 v32, v36, v37
	v_cvt_pk_bf16_f32 v33, v38, v39
	v_cvt_pk_bf16_f32 v34, v40, v41
	v_cvt_pk_bf16_f32 v35, v42, v35
	global_store_dwordx4 v[46:47], v[32:35], off
	v_lshl_add_u64 v[38:39], v[98:99], 0, v[168:169]
	v_lshl_add_u64 v[36:37], v[96:97], 0, v[168:169]
	s_waitcnt vmcnt(11)
	v_mov_b32_e32 v32, v218
	v_mov_b32_e32 v33, v219
	v_mov_b32_e32 v34, v220
	v_mov_b32_e32 v35, v221
	v_lshlrev_b32_e32 v43, 16, v35
	v_and_b32_e32 v35, 0xffff0000, v35
	v_lshlrev_b32_e32 v40, 16, v32
	v_and_b32_e32 v32, 0xffff0000, v32
	v_lshlrev_b32_e32 v41, 16, v33
	v_and_b32_e32 v33, 0xffff0000, v33
	v_lshlrev_b32_e32 v42, 16, v34
	v_and_b32_e32 v34, 0xffff0000, v34
	v_mul_f32_e32 v51, 0xbfb8aa3b, v35
	v_mul_f32_e32 v44, 0xbfb8aa3b, v40
	v_mul_f32_e32 v45, 0xbfb8aa3b, v32
	v_mul_f32_e32 v46, 0xbfb8aa3b, v41
	v_mul_f32_e32 v47, 0xbfb8aa3b, v33
	v_mul_f32_e32 v48, 0xbfb8aa3b, v42
	v_mul_f32_e32 v49, 0xbfb8aa3b, v34
	v_mul_f32_e32 v50, 0xbfb8aa3b, v43
	v_exp_f32_e32 v51, v51
	v_exp_f32_e32 v44, v44
	v_exp_f32_e32 v45, v45
	v_exp_f32_e32 v46, v46
	v_exp_f32_e32 v47, v47
	v_exp_f32_e32 v48, v48
	v_exp_f32_e32 v49, v49
	v_exp_f32_e32 v50, v50
	v_add_f32_e32 v51, 1.0, v51
	v_add_f32_e32 v44, 1.0, v44
	v_add_f32_e32 v45, 1.0, v45
	v_add_f32_e32 v46, 1.0, v46
	v_add_f32_e32 v47, 1.0, v47
	v_add_f32_e32 v48, 1.0, v48
	v_add_f32_e32 v49, 1.0, v49
	v_add_f32_e32 v50, 1.0, v50
	v_rcp_f32_e32 v51, v51
	v_rcp_f32_e32 v44, v44
	v_rcp_f32_e32 v45, v45
	v_rcp_f32_e32 v46, v46
	v_rcp_f32_e32 v47, v47
	v_rcp_f32_e32 v48, v48
	v_rcp_f32_e32 v49, v49
	v_rcp_f32_e32 v50, v50
	v_mul_f32_e32 v35, v51, v35
	v_mul_f32_e32 v40, v44, v40
	v_mul_f32_e32 v32, v45, v32
	v_mul_f32_e32 v41, v46, v41
	v_mul_f32_e32 v33, v47, v33
	v_mul_f32_e32 v42, v48, v42
	v_mul_f32_e32 v34, v49, v34
	v_mul_f32_e32 v43, v50, v43
	v_mul_f32_e32 v27, v27, v35
	v_mul_f32_e32 v28, v28, v40
	v_mul_f32_e32 v29, v29, v32
	v_mul_f32_e32 v30, v30, v41
	v_mul_f32_e32 v31, v31, v33
	v_mul_f32_e32 v32, v24, v42
	v_mul_f32_e32 v33, v25, v34
	v_mul_f32_e32 v34, v26, v43
	v_cvt_pk_bf16_f32 v24, v28, v29
	v_cvt_pk_bf16_f32 v25, v30, v31
	v_cvt_pk_bf16_f32 v26, v32, v33
	v_cvt_pk_bf16_f32 v27, v34, v27
	global_store_dwordx4 v[38:39], v[24:27], off
	v_lshl_add_u64 v[30:31], v[90:91], 0, v[168:169]
	v_lshl_add_u64 v[28:29], v[88:89], 0, v[168:169]
	s_waitcnt vmcnt(10)
; __device__ __forceinline__ float bflo(unsigned w) { return __uint_as_float(w << 16); }
; __device__ __forceinline__ float bfhi(unsigned w) { return __uint_as_float(w & 0xffff0000u); }
; __device__ __forceinline__ unsigned pk2(float lo, float hi) { unsigned r; asm("v_cvt_pk_bf16_f32 %0, %1, %2" : "=v"(r) : "v"(lo), "v"(hi)); return r; }
; __device__ __forceinline__ float siluf_(float x) { return x * __builtin_amdgcn_rcpf(1.0f + __expf(-x)); }
; #define PG8_WAIT_V(n) asm volatile("s_waitcnt vmcnt(" #n ")" ::: "memory")
; #define PG8_BAR __builtin_amdgcn_s_barrier()
; template <class Epi>
; __device__ __forceinline__ void gemm_phase(LAS unsigned char* lds, const GemmD g, const Epi& E) {
;     ...
;     PG8_WAIT_V(0);
;     if (wr == 0) PG8_BAR;
;     PG8_BAR;
;     __device__ __forceinline__ void operator()(const f32x4 (&acc)[2][2][4][2], const Unit& u, int wr, int wc, int fr, int fq) const {
;     ...
;                 for (int m = 0; m < 4; ++m) { const int row = row0 + ai * HALF + m * 16;
;                     const u32x4 z = __builtin_nontemporal_load((const u32x4*)(proj + (size_t)row * NPROJ + C_ZP + col));
;                     f32x4 v0 = (acc[ai][bj][m][0] + b0) * s0, v1 = (acc[ai][bj][m][1] + b1) * s1;
;                     v0[0] *= siluf_(bflo(z.x)); v0[1] *= siluf_(bfhi(z.x)); v0[2] *= siluf_(bflo(z.y)); v0[3] *= siluf_(bfhi(z.y));
;                     v1[0] *= siluf_(bflo(z.z)); v1[1] *= siluf_(bfhi(z.z)); v1[2] *= siluf_(bflo(z.w)); v1[3] *= siluf_(bfhi(z.w));
;                     u32x4 w; w.x = pk2(v0[0], v0[1]); w.y = pk2(v0[2], v0[3]); w.z = pk2(v1[0], v1[1]); w.w = pk2(v1[2], v1[3]);
;                     *(u32x4*)(a2 + (size_t)row * 4096 + 2048 + col) = w; } }
	v_mov_b32_e32 v24, v222
	v_mov_b32_e32 v25, v223
	v_mov_b32_e32 v26, v224
	v_mov_b32_e32 v27, v225
	v_lshlrev_b32_e32 v35, 16, v27
	v_and_b32_e32 v27, 0xffff0000, v27
	v_lshlrev_b32_e32 v32, 16, v24
	v_and_b32_e32 v24, 0xffff0000, v24
	v_lshlrev_b32_e32 v33, 16, v25
	v_and_b32_e32 v25, 0xffff0000, v25
	v_lshlrev_b32_e32 v34, 16, v26
	v_and_b32_e32 v26, 0xffff0000, v26
	v_mul_f32_e32 v43, 0xbfb8aa3b, v27
	v_mul_f32_e32 v36, 0xbfb8aa3b, v32
	v_mul_f32_e32 v37, 0xbfb8aa3b, v24
	v_mul_f32_e32 v38, 0xbfb8aa3b, v33
	v_mul_f32_e32 v39, 0xbfb8aa3b, v25
	v_mul_f32_e32 v40, 0xbfb8aa3b, v34
	v_mul_f32_e32 v41, 0xbfb8aa3b, v26
	v_mul_f32_e32 v42, 0xbfb8aa3b, v35
	v_exp_f32_e32 v43, v43
	v_exp_f32_e32 v36, v36
	v_exp_f32_e32 v37, v37
	v_exp_f32_e32 v38, v38
	v_exp_f32_e32 v39, v39
	v_exp_f32_e32 v40, v40
	v_exp_f32_e32 v41, v41
	v_exp_f32_e32 v42, v42
	v_add_f32_e32 v43, 1.0, v43
	v_add_f32_e32 v36, 1.0, v36
	v_add_f32_e32 v37, 1.0, v37
	v_add_f32_e32 v38, 1.0, v38
	v_add_f32_e32 v39, 1.0, v39
	v_add_f32_e32 v40, 1.0, v40
	v_add_f32_e32 v41, 1.0, v41
	v_add_f32_e32 v42, 1.0, v42
	v_rcp_f32_e32 v43, v43
	v_rcp_f32_e32 v36, v36
	v_rcp_f32_e32 v37, v37
	v_rcp_f32_e32 v38, v38
	v_rcp_f32_e32 v39, v39
	v_rcp_f32_e32 v40, v40
	v_rcp_f32_e32 v41, v41
	v_rcp_f32_e32 v42, v42
	v_mul_f32_e32 v27, v43, v27
	v_mul_f32_e32 v32, v36, v32
	v_mul_f32_e32 v24, v37, v24
	v_mul_f32_e32 v33, v38, v33
	v_mul_f32_e32 v25, v39, v25
	v_mul_f32_e32 v34, v40, v34
	v_mul_f32_e32 v26, v41, v26
	v_mul_f32_e32 v35, v42, v35
	v_mul_f32_e32 v19, v19, v27
	v_mul_f32_e32 v20, v20, v32
	v_mul_f32_e32 v21, v21, v24
	v_mul_f32_e32 v22, v22, v33
	v_mul_f32_e32 v23, v23, v25
	v_mul_f32_e32 v24, v16, v34
	v_mul_f32_e32 v25, v17, v26
	v_mul_f32_e32 v26, v18, v35
	v_cvt_pk_bf16_f32 v16, v20, v21
	v_cvt_pk_bf16_f32 v17, v22, v23
	v_cvt_pk_bf16_f32 v18, v24, v25
	v_cvt_pk_bf16_f32 v19, v26, v19
	global_store_dwordx4 v[30:31], v[16:19], off
	v_lshl_add_u64 v[22:23], v[84:85], 0, v[168:169]
	v_lshl_add_u64 v[20:21], v[82:83], 0, v[168:169]
	s_waitcnt vmcnt(9)
	v_mov_b32_e32 v16, v226
	v_mov_b32_e32 v17, v227
	v_mov_b32_e32 v18, v228
	v_mov_b32_e32 v19, v229
	v_lshlrev_b32_e32 v27, 16, v19
	v_and_b32_e32 v19, 0xffff0000, v19
	v_lshlrev_b32_e32 v24, 16, v16
	v_and_b32_e32 v16, 0xffff0000, v16
	v_lshlrev_b32_e32 v25, 16, v17
	v_and_b32_e32 v17, 0xffff0000, v17
	v_lshlrev_b32_e32 v26, 16, v18
	v_and_b32_e32 v18, 0xffff0000, v18
	v_mul_f32_e32 v35, 0xbfb8aa3b, v19
	v_mul_f32_e32 v28, 0xbfb8aa3b, v24
	v_mul_f32_e32 v29, 0xbfb8aa3b, v16
	v_mul_f32_e32 v30, 0xbfb8aa3b, v25
	v_mul_f32_e32 v31, 0xbfb8aa3b, v17
	v_mul_f32_e32 v32, 0xbfb8aa3b, v26
	v_mul_f32_e32 v33, 0xbfb8aa3b, v18
	v_mul_f32_e32 v34, 0xbfb8aa3b, v27
	v_exp_f32_e32 v35, v35
	v_exp_f32_e32 v28, v28
	v_exp_f32_e32 v29, v29
	v_exp_f32_e32 v30, v30
	v_exp_f32_e32 v31, v31
	v_exp_f32_e32 v32, v32
	v_exp_f32_e32 v33, v33
	v_exp_f32_e32 v34, v34
	v_add_f32_e32 v35, 1.0, v35
	v_add_f32_e32 v28, 1.0, v28
	v_add_f32_e32 v29, 1.0, v29
	v_add_f32_e32 v30, 1.0, v30
	v_add_f32_e32 v31, 1.0, v31
	v_add_f32_e32 v32, 1.0, v32
	v_add_f32_e32 v33, 1.0, v33
	v_add_f32_e32 v34, 1.0, v34
	v_rcp_f32_e32 v35, v35
	v_rcp_f32_e32 v28, v28
	v_rcp_f32_e32 v29, v29
	v_rcp_f32_e32 v30, v30
	v_rcp_f32_e32 v31, v31
	v_rcp_f32_e32 v32, v32
	v_rcp_f32_e32 v33, v33
	v_rcp_f32_e32 v34, v34
	v_mul_f32_e32 v19, v35, v19
	v_mul_f32_e32 v24, v28, v24
	v_mul_f32_e32 v16, v29, v16
	v_mul_f32_e32 v25, v30, v25
	v_mul_f32_e32 v17, v31, v17
	v_mul_f32_e32 v26, v32, v26
	v_mul_f32_e32 v18, v33, v18
	v_mul_f32_e32 v27, v34, v27
	v_mul_f32_e32 v11, v11, v19
	v_mul_f32_e32 v12, v12, v24
	v_mul_f32_e32 v13, v13, v16
	v_mul_f32_e32 v14, v14, v25
	v_mul_f32_e32 v15, v15, v17
	v_mul_f32_e32 v16, v8, v26
	v_mul_f32_e32 v17, v9, v18
	v_mul_f32_e32 v18, v10, v27
	v_cvt_pk_bf16_f32 v8, v12, v13
	v_cvt_pk_bf16_f32 v9, v14, v15
	v_cvt_pk_bf16_f32 v10, v16, v17
	v_cvt_pk_bf16_f32 v11, v18, v11
	global_store_dwordx4 v[22:23], v[8:11], off
	v_lshl_add_u64 v[12:13], v[80:81], 0, v[168:169]
	s_waitcnt vmcnt(8)
	v_mov_b32_e32 v8, v230
	v_mov_b32_e32 v9, v231
	v_mov_b32_e32 v10, v232
	v_mov_b32_e32 v11, v233
	v_lshlrev_b32_e32 v17, 16, v11
	v_and_b32_e32 v11, 0xffff0000, v11
	v_lshlrev_b32_e32 v14, 16, v8
	v_and_b32_e32 v8, 0xffff0000, v8
	v_lshlrev_b32_e32 v15, 16, v9
	v_and_b32_e32 v9, 0xffff0000, v9
	v_lshlrev_b32_e32 v16, 16, v10
	v_and_b32_e32 v10, 0xffff0000, v10
	v_mul_f32_e32 v25, 0xbfb8aa3b, v11
	v_mul_f32_e32 v18, 0xbfb8aa3b, v14
	v_mul_f32_e32 v19, 0xbfb8aa3b, v8
	v_mul_f32_e32 v20, 0xbfb8aa3b, v15
	v_mul_f32_e32 v21, 0xbfb8aa3b, v9
	v_mul_f32_e32 v22, 0xbfb8aa3b, v16
	v_mul_f32_e32 v23, 0xbfb8aa3b, v10
	v_mul_f32_e32 v24, 0xbfb8aa3b, v17
	v_exp_f32_e32 v25, v25
	v_exp_f32_e32 v18, v18
	v_exp_f32_e32 v19, v19
	v_exp_f32_e32 v20, v20
	v_exp_f32_e32 v21, v21
	v_exp_f32_e32 v22, v22
	v_exp_f32_e32 v23, v23
	v_exp_f32_e32 v24, v24
	v_add_f32_e32 v25, 1.0, v25
	v_add_f32_e32 v18, 1.0, v18
	v_add_f32_e32 v19, 1.0, v19
	v_add_f32_e32 v20, 1.0, v20
	v_add_f32_e32 v21, 1.0, v21
	v_add_f32_e32 v22, 1.0, v22
	v_add_f32_e32 v23, 1.0, v23
	v_add_f32_e32 v24, 1.0, v24
	v_rcp_f32_e32 v25, v25
	v_rcp_f32_e32 v18, v18
	v_rcp_f32_e32 v19, v19
	v_rcp_f32_e32 v20, v20
	v_rcp_f32_e32 v21, v21
	v_rcp_f32_e32 v22, v22
	v_rcp_f32_e32 v23, v23
	v_rcp_f32_e32 v24, v24
	v_mul_f32_e32 v11, v25, v11
	v_mul_f32_e32 v14, v18, v14
	v_mul_f32_e32 v8, v19, v8
	v_mul_f32_e32 v15, v20, v15
	v_mul_f32_e32 v9, v21, v9
	v_mul_f32_e32 v16, v22, v16
	v_mul_f32_e32 v10, v23, v10
	v_mul_f32_e32 v17, v24, v17
	v_mul_f32_e32 v3, v3, v11
	v_mul_f32_e32 v4, v4, v14
	v_mul_f32_e32 v5, v5, v8
	v_mul_f32_e32 v6, v6, v15
	v_mul_f32_e32 v7, v7, v9
	v_mul_f32_e32 v8, v0, v16
	v_mul_f32_e32 v9, v1, v10
	v_mul_f32_e32 v10, v2, v17
	v_cvt_pk_bf16_f32 v0, v4, v5
	v_cvt_pk_bf16_f32 v1, v6, v7
	v_cvt_pk_bf16_f32 v2, v8, v9
	v_cvt_pk_bf16_f32 v3, v10, v3
	global_store_dwordx4 v[12:13], v[0:3], off
	s_cbranch_vccz .LBB0_595
	s_waitcnt vmcnt(0)
	s_cmpk_gt_u32 s33, 0xff
	s_cbranch_scc1 .LBB0_604
	s_barrier

; __device__ __forceinline__ unsigned xb_ld(unsigned* p)              { return __hip_atomic_load(p, __ATOMIC_RELAXED, __HIP_MEMORY_SCOPE_AGENT); }
; __device__ __forceinline__ unsigned xb_add(unsigned* p, unsigned v) { return __hip_atomic_fetch_add(p, v, __ATOMIC_RELAXED, __HIP_MEMORY_SCOPE_AGENT); }
; #define XB_SPIN(cond, bar) do { unsigned _sp = 0; while (cond) { __builtin_amdgcn_s_sleep(1); \
;     if ((++_sp & 255u) == 0u) { if (xb_ld(&(bar)[XB_TMO])) break; if (_sp > XB_SPIN_CAP) { atomicAdd(&(bar)[XB_TMO], 1u); break; } } } } while (0)
; __device__ __forceinline__ void xcd_barrier(const XcdBarrier& b) {
;     ...
;         const unsigned old = xb_add(&bar[XB_XSUB(b.x)], 1u);
;         const unsigned gen = old / nloc;
;         if (old + 1u == (gen + 1u) * nloc) {
;             __builtin_amdgcn_fence(__ATOMIC_RELEASE, "agent");
;             asm volatile("s_waitcnt vmcnt(0)" ::: "memory");
;             const unsigned og = xb_add(&bar[XB_TOP], 1u);
;             const unsigned tg = og / nx;
;             if (og + 1u == (tg + 1u) * nx) xb_add(&bar[XB_TOPGEN], 1u);
;             else XB_SPIN(xb_ld(&bar[XB_TOPGEN]) == tg, bar);
;             __builtin_amdgcn_fence(__ATOMIC_ACQUIRE, "agent");
;             xb_add(&bar[XB_XGEN(b.x)], 1u);
;             asm volatile("s_waitcnt vmcnt(0)" ::: "memory");
;         } else {
;             XB_SPIN(xb_ld(&bar[XB_XGEN(b.x)]) == gen, bar);
.LBB0_630:
	s_or_b64 exec, exec, s[8:9]
	v_cvt_f32_u32_e32 v4, v2
	buffer_inv sc1
	s_waitcnt vmcnt(1)
	v_readfirstlane_b32 s2, v3
	v_sub_u32_e32 v3, 0, v2
	s_lshl_b32 s4, s22, 6
	v_rcp_iflag_f32_e32 v4, v4
	v_add_u32_e32 v5, s2, v1
	v_mul_f32_e32 v4, 0x4f7ffffe, v4
	v_cvt_u32_f32_e32 v4, v4
	v_mul_lo_u32 v1, v3, v4
	v_mul_hi_u32 v1, v4, v1
	v_add_u32_e32 v1, v4, v1
	v_mul_hi_u32 v1, v5, v1
	v_mul_lo_u32 v3, v1, v2
	v_sub_u32_e32 v3, v5, v3
	v_add_u32_e32 v4, 1, v1
	v_cmp_ge_u32_e32 vcc, v3, v2
	s_nop 1
	v_cndmask_b32_e32 v1, v1, v4, vcc
	v_sub_u32_e32 v4, v3, v2
	v_cndmask_b32_e32 v3, v3, v4, vcc
	v_add_u32_e32 v4, 1, v1
	v_cmp_ge_u32_e32 vcc, v3, v2
	v_add_u32_e32 v3, 1, v5
	s_nop 0
	v_cndmask_b32_e32 v1, v1, v4, vcc
	v_mul_lo_u32 v4, v2, v1
	v_add_u32_e32 v2, v4, v2
	v_cmp_ne_u32_e32 vcc, v3, v2
	s_and_saveexec_b64 s[2:3], vcc
	s_xor_b64 s[8:9], exec, s[2:3]
	s_cbranch_execz .LBB0_644
	s_waitcnt lgkmcnt(0)
	v_mov_b32_e32 v0, 0x2000
	global_load_dword v0, v0, s[6:7] offset:1024 sc1
	s_add_u32 s14, s6, 0x2400
	s_addc_u32 s15, s7, 0
	s_waitcnt vmcnt(0)
	v_cmp_eq_u32_e32 vcc, v0, v1
	s_and_saveexec_b64 s[10:11], vcc
	s_cbranch_execz .LBB0_643
	s_add_u32 s12, s88, 0x1fa60200
	s_addc_u32 s13, s89, 0
	s_mov_b32 s2, 1
	s_mov_b64 s[24:25], 0
	v_mov_b32_e32 v0, 0
	s_branch .LBB0_634

; __device__ __forceinline__ unsigned xb_ld(unsigned* p)              { return __hip_atomic_load(p, __ATOMIC_RELAXED, __HIP_MEMORY_SCOPE_AGENT); }
; #define XB_SPIN(cond, bar) do { unsigned _sp = 0; while (cond) { __builtin_amdgcn_s_sleep(1); \
;     if ((++_sp & 255u) == 0u) { if (xb_ld(&(bar)[XB_TMO])) break; if (_sp > XB_SPIN_CAP) { atomicAdd(&(bar)[XB_TMO], 1u); break; } } } } while (0)
; __device__ __forceinline__ void xcd_barrier(const XcdBarrier& b) {
;     ...
;             XB_SPIN(xb_ld(&bar[XB_XGEN(b.x)]) == gen, bar);
;             __builtin_amdgcn_fence(__ATOMIC_ACQUIRE, "agent");
;             asm volatile("s_waitcnt vmcnt(0)" ::: "memory");
.LBB0_643:
	s_or_b64 exec, exec, s[10:11]
	s_waitcnt vmcnt(0)
	s_nop 0
	s_waitcnt vmcnt(0)

; __device__ __forceinline__ unsigned xb_ld(unsigned* p)              { return __hip_atomic_load(p, __ATOMIC_RELAXED, __HIP_MEMORY_SCOPE_AGENT); }
; __device__ __forceinline__ unsigned xb_add(unsigned* p, unsigned v) { return __hip_atomic_fetch_add(p, v, __ATOMIC_RELAXED, __HIP_MEMORY_SCOPE_AGENT); }
; #define XB_SPIN(cond, bar) do { unsigned _sp = 0; while (cond) { __builtin_amdgcn_s_sleep(1); \
;     if ((++_sp & 255u) == 0u) { if (xb_ld(&(bar)[XB_TMO])) break; if (_sp > XB_SPIN_CAP) { atomicAdd(&(bar)[XB_TMO], 1u); break; } } } } while (0)
; __device__ __forceinline__ void xcd_barrier(const XcdBarrier& b) {
;     ...
;             if (og + 1u == (tg + 1u) * nx) xb_add(&bar[XB_TOPGEN], 1u);
;             else XB_SPIN(xb_ld(&bar[XB_TOPGEN]) == tg, bar);
;             __builtin_amdgcn_fence(__ATOMIC_ACQUIRE, "agent");
;             xb_add(&bar[XB_XGEN(b.x)], 1u);
;             asm volatile("s_waitcnt vmcnt(0)" ::: "memory");
.LBB0_661:
	s_or_b64 exec, exec, s[10:11]
	s_mov_b64 s[2:3], exec
	v_mbcnt_lo_u32_b32 v0, s2, 0
	v_mbcnt_hi_u32_b32 v0, s3, v0
	v_cmp_eq_u32_e32 vcc, 0, v0
	s_waitcnt vmcnt(0)
	s_nop 0
	s_and_saveexec_b64 s[10:11], vcc
	s_cbranch_execz .LBB0_663
	s_bcnt1_i32_b64 s2, s[2:3]
	v_mov_b32_e32 v0, 0x2000
	v_mov_b32_e32 v1, s2
	global_atomic_add v0, v1, s[6:7] offset:1024

; __device__ __forceinline__ unsigned xb_add(unsigned* p, unsigned v) { return __hip_atomic_fetch_add(p, v, __ATOMIC_RELAXED, __HIP_MEMORY_SCOPE_AGENT); }
; __device__ __forceinline__ void xcd_barrier(const XcdBarrier& b) {
;     ...
;             __builtin_amdgcn_fence(__ATOMIC_ACQUIRE, "agent");
;             xb_add(&bar[XB_XGEN(b.x)], 1u);
;             asm volatile("s_waitcnt vmcnt(0)" ::: "memory");
.LBB0_666:
	s_or_b64 exec, exec, s[2:3]
	s_waitcnt vmcnt(0)
	s_nop 0
	global_atomic_add v[174:175], v202, off
	s_waitcnt vmcnt(0)

; __device__ __forceinline__ unsigned xb_ld(unsigned* p)              { return __hip_atomic_load(p, __ATOMIC_RELAXED, __HIP_MEMORY_SCOPE_AGENT); }
; __device__ __forceinline__ unsigned xb_add(unsigned* p, unsigned v) { return __hip_atomic_fetch_add(p, v, __ATOMIC_RELAXED, __HIP_MEMORY_SCOPE_AGENT); }
; #define XB_SPIN(cond, bar) do { unsigned _sp = 0; while (cond) { __builtin_amdgcn_s_sleep(1); \
;     if ((++_sp & 255u) == 0u) { if (xb_ld(&(bar)[XB_TMO])) break; if (_sp > XB_SPIN_CAP) { atomicAdd(&(bar)[XB_TMO], 1u); break; } } } } while (0)
; __device__ __forceinline__ void xcd_barrier(const XcdBarrier& b) {
;     ...
;         const unsigned old = xb_add(&bar[XB_XSUB(b.x)], 1u);
;         const unsigned gen = old / nloc;
;         if (old + 1u == (gen + 1u) * nloc) {
;             __builtin_amdgcn_fence(__ATOMIC_RELEASE, "agent");
;             asm volatile("s_waitcnt vmcnt(0)" ::: "memory");
;             const unsigned og = xb_add(&bar[XB_TOP], 1u);
;             const unsigned tg = og / nx;
;             if (og + 1u == (tg + 1u) * nx) xb_add(&bar[XB_TOPGEN], 1u);
;             else XB_SPIN(xb_ld(&bar[XB_TOPGEN]) == tg, bar);
;             __builtin_amdgcn_fence(__ATOMIC_ACQUIRE, "agent");
;             xb_add(&bar[XB_XGEN(b.x)], 1u);
;             asm volatile("s_waitcnt vmcnt(0)" ::: "memory");
;         } else {
;             XB_SPIN(xb_ld(&bar[XB_XGEN(b.x)]) == gen, bar);
.LBB0_930:
	global_atomic_add v4, v[172:173], v202, off sc0
	v_cvt_f32_u32_e32 v0, v3
	v_sub_u32_e32 v5, 0, v3
	v_rcp_iflag_f32_e32 v0, v0
	s_nop 0
	v_mul_f32_e32 v0, 0x4f7ffffe, v0
	v_cvt_u32_f32_e32 v0, v0
	v_mul_lo_u32 v5, v5, v0
	v_mul_hi_u32 v5, v0, v5
	v_add_u32_e32 v0, v0, v5
	buffer_inv sc1
	s_waitcnt vmcnt(1)
	v_mul_hi_u32 v0, v4, v0
	v_mul_lo_u32 v5, v0, v3
	v_sub_u32_e32 v5, v4, v5
	v_add_u32_e32 v6, 1, v0
	v_cmp_ge_u32_e32 vcc, v5, v3
	v_add_u32_e32 v4, 1, v4
	s_nop 0
	v_cndmask_b32_e32 v0, v0, v6, vcc
	v_sub_u32_e32 v6, v5, v3
	v_cndmask_b32_e32 v5, v5, v6, vcc
	v_add_u32_e32 v6, 1, v0
	v_cmp_ge_u32_e32 vcc, v5, v3
	s_nop 1
	v_cndmask_b32_e32 v0, v0, v6, vcc
	v_mul_lo_u32 v5, v3, v0
	v_add_u32_e32 v3, v5, v3
	v_cmp_ne_u32_e32 vcc, v4, v3
	s_and_saveexec_b64 s[2:3], vcc
	s_xor_b64 s[24:25], exec, s[2:3]
	s_cbranch_execz .LBB0_944
	s_waitcnt lgkmcnt(0)
	global_load_dword v2, v[174:175], off sc1
	s_waitcnt vmcnt(0)
	v_cmp_eq_u32_e32 vcc, v2, v0
	s_and_saveexec_b64 s[26:27], vcc
	s_cbranch_execz .LBB0_943
	s_mov_b32 s2, 1
	s_mov_b64 s[28:29], 0
	s_branch .LBB0_934

; __device__ __forceinline__ unsigned xb_ld(unsigned* p)              { return __hip_atomic_load(p, __ATOMIC_RELAXED, __HIP_MEMORY_SCOPE_AGENT); }
; #define XB_SPIN(cond, bar) do { unsigned _sp = 0; while (cond) { __builtin_amdgcn_s_sleep(1); \
;     if ((++_sp & 255u) == 0u) { if (xb_ld(&(bar)[XB_TMO])) break; if (_sp > XB_SPIN_CAP) { atomicAdd(&(bar)[XB_TMO], 1u); break; } } } } while (0)
; __device__ __forceinline__ void xcd_barrier(const XcdBarrier& b) {
;     ...
;             XB_SPIN(xb_ld(&bar[XB_XGEN(b.x)]) == gen, bar);
;             __builtin_amdgcn_fence(__ATOMIC_ACQUIRE, "agent");
;             asm volatile("s_waitcnt vmcnt(0)" ::: "memory");
.LBB0_943:
	s_or_b64 exec, exec, s[26:27]
	s_waitcnt vmcnt(0)
	s_nop 0
	s_waitcnt vmcnt(0)
